# added: rw_phaseC item-start loads batched, R1 token-shift loads hoisted to row start (one wait per row), rw_phaseB pre-state stores issued after the MFMAs
# speedup vs baseline: 1.0364x; 1.0077x over previous
; __device__ __forceinline__ float siluf_(float x) { return x * __builtin_amdgcn_rcpf(1.0f + __expf(-x)); }
; __global__ void __launch_bounds__(NTHREADS, 2) fwd_megakernel(Args args) {
;     ...
;         for (int r = gw; r < M; r += NGW) {
;             const int b = r / T, t = r - b * T;
;             const bf16_t* pr = PROJ + (size_t)r * NP;
; #pragma unroll
;             for (int it = 0; it < 2; ++it) {
;                 const int c8 = (it * 64 + lane) * 8;
;                 float o[8];
; #pragma unroll
;                 for (int i = 0; i < 8; ++i) o[i] = 0.f;
; #pragma unroll
;                 for (int j = 0; j < 4; ++j) {
;                     if (t - 3 + j >= 0) {
;                         float xv[8]; unpack8(*(const u32x4*)(pr - (size_t)(3 - j) * NP + C_BQ + c8), xv);
;                         const float* wp = mconv + ((size_t)l * 4 + j) * 1024 + c8;
;                         const f32x4 w0v = *(const f32x4*)wp, w1v = *(const f32x4*)(wp + 4);
; #pragma unroll
;                         for (int i = 0; i < 4; ++i) { o[i] += w0v[i] * xv[i]; o[4 + i] += w1v[i] * xv[4 + i]; }
;                     }
;                 }
;                 const float sc = (c8 < 512) ? 0.08838834764831845f : 1.0f;
; #pragma unroll
;                 for (int i = 0; i < 8; ++i) o[i] = siluf_(o[i]) * sc;
;                 *(u32x4*)(BQK + (size_t)r * 1024 + c8) = pack8(o);
;             }
;             if (lane < 8) {
;                 const float raw = IGFG[(size_t)r * 8 + lane];
;                 float o;
;                 if (lane < 4) o = raw + ig_b[l * 4 + lane];
;                 else { const float z = raw + fg_b[l * 4 + (lane - 4)]; o = fminf(z, 0.f) - __logf(1.0f + __expf(-fabsf(z))); }
;                 IL[(size_t)r * 8 + lane] = o;
;             }
; #pragma unroll
;             for (int it = 0; it < 6; ++it) {
;                 const int c8 = (it * 64 + lane) * 8;
;                 float cur[8], prv[8], o[8];
;                 unpack8(*(const u32x4*)(pr + C_CR + c8), cur);
;                 if (t > 0) unpack8(*(const u32x4*)(pr - NP + C_CR + c8), prv);
;                 else {
; #pragma unroll
;                     for (int i = 0; i < 8; ++i) prv[i] = 0.f;
;                 }
;                 const float* mp = mu + (size_t)l * 3200 + c8;
;                 const f32x4 m0 = *(const f32x4*)mp, m1 = *(const f32x4*)(mp + 4);
; #pragma unroll
.LBB0_411:
	v_mul_hi_i32 v0, v60, s14
	v_lshrrev_b32_e32 v1, 31, v0
	v_ashrrev_i32_e32 v0, 12, v0
	v_add_u32_e32 v0, v0, v1
	v_mul_i32_i24_e32 v0, 0x2010, v0
	v_sub_u32_e32 v5, v60, v0
	v_mov_b64_e32 v[0:1], s[78:79]
	v_mov_b32_e32 v62, 0
	v_mad_i64_i32 v[66:67], s[0:1], v60, s58, v[0:1]
	v_and_b32_e32 v100, 63, v226
	v_lshlrev_b32_e32 v100, 4, v100
	v_mov_b32_e32 v101, 0
	v_lshl_add_u64 v[224:225], v[66:67], 0, v[100:101]
	s_mov_b64 s[100:101], 0x4000
	v_lshl_add_u64 v[140:141], v[224:225], 0, s[100:101]
	global_load_dwordx4 v[154:157], v[140:141], off
	global_load_dwordx4 v[158:161], v[140:141], off offset:1024
	global_load_dwordx4 v[162:165], v[140:141], off offset:2048
	global_load_dwordx4 v[166:169], v[140:141], off offset:3072
	s_mov_b64 s[100:101], 0x5000
	v_lshl_add_u64 v[140:141], v[224:225], 0, s[100:101]
	global_load_dwordx4 v[170:173], v[140:141], off
	global_load_dwordx4 v[174:177], v[140:141], off offset:1024
	s_mov_b32 s100, 0xffffae00
	s_mov_b32 s101, -1
	v_lshl_add_u64 v[140:141], v[224:225], 0, s[100:101]
	global_load_dwordx4 v[178:181], v[140:141], off
	global_load_dwordx4 v[182:185], v[140:141], off offset:1024
	global_load_dwordx4 v[188:191], v[140:141], off offset:2048
	global_load_dwordx4 v[192:195], v[140:141], off offset:3072
	s_mov_b32 s100, 0xffffbe00
	s_mov_b32 s101, -1
	v_lshl_add_u64 v[140:141], v[224:225], 0, s[100:101]
	global_load_dwordx4 v[196:199], v[140:141], off
	global_load_dwordx4 v[200:203], v[140:141], off offset:1024
	global_load_dwordx4 v[204:207], v[16:17], off offset:16
	global_load_dwordx4 v[208:211], v[16:17], off
	global_load_dwordx4 v[212:215], v[16:17], off offset:2064
	global_load_dwordx4 v[216:219], v[16:17], off offset:2048
	global_load_dwordx4 v[220:223], v[38:39], off offset:16
	global_load_dwordx4 v[96:99], v[38:39], off
	global_load_dwordx4 v[102:105], v[42:43], off offset:16
	global_load_dwordx4 v[106:109], v[42:43], off
	global_load_dwordx4 v[110:113], v[46:47], off offset:16
	global_load_dwordx4 v[116:119], v[46:47], off
	global_load_dwordx4 v[120:123], v[50:51], off offset:16
	global_load_dwordx4 v[136:139], v[50:51], off
	v_cmp_lt_i32_e64 s[46:47], 2, v5
	v_lshlrev_b32_e32 v54, 1, v6
	v_mov_b32_e32 v63, 0
	v_mov_b32_e32 v56, 0
	v_mov_b32_e32 v57, 0
	v_mov_b32_e32 v2, 0
	v_mov_b32_e32 v3, v62
	v_mov_b32_e32 v0, v62
	v_mov_b32_e32 v1, v62
	v_mov_b32_e32 v58, 0
	v_mov_b32_e32 v59, 0
	s_and_saveexec_b64 s[0:1], s[46:47]
	s_cbranch_execnz .LBB0_552
	s_or_b64 exec, exec, s[0:1]
	v_cmp_lt_i32_e64 s[48:49], 1, v5
	s_and_saveexec_b64 s[0:1], s[48:49]
	s_cbranch_execnz .LBB0_553

; __global__ void __launch_bounds__(NTHREADS, 2) fwd_megakernel(Args args) {
;     ...
;             for (int it = 0; it < 6; ++it) {
;                 const int c8 = (it * 64 + lane) * 8;
;                 float cur[8], prv[8], o[8];
;                 unpack8(*(const u32x4*)(pr + C_CR + c8), cur);
;                 if (t > 0) unpack8(*(const u32x4*)(pr - NP + C_CR + c8), prv);
;                 else {
; #pragma unroll
;                     for (int i = 0; i < 8; ++i) prv[i] = 0.f;
;                 }
;                 const float* mp = mu + (size_t)l * 3200 + c8;
;                 const f32x4 m0 = *(const f32x4*)mp, m1 = *(const f32x4*)(mp + 4);
; #pragma unroll
;                 for (int i = 0; i < 4; ++i) { o[i] = cur[i] + (prv[i] - cur[i]) * m0[i]; o[4 + i] = cur[4 + i] + (prv[4 + i] - cur[4 + i]) * m1[i]; }
;                 *(u32x4*)(CRKV + (size_t)r * 3072 + c8) = pack8(o);
;             }
.LBB0_427:
	s_or_b64 exec, exec, s[46:47]
	s_mov_b64 s[0:1], 0x4000
	v_lshl_add_u64 v[72:73], v[66:67], 0, s[0:1]
	v_mov_b32_e32 v55, v9
	v_lshl_add_u64 v[0:1], v[72:73], 0, v[54:55]
	s_waitcnt vmcnt(0)
	v_mov_b32_e32 v0, v154
	v_mov_b32_e32 v1, v155
	v_mov_b32_e32 v2, v156
	v_mov_b32_e32 v3, v157
	s_movk_i32 s0, 0xae00
	s_mov_b32 s1, -1
	v_lshl_add_u64 v[70:71], v[66:67], 0, s[0:1]
	v_mov_b32_e32 v58, 0
	v_mov_b32_e32 v74, 0
	v_mov_b32_e32 v75, 0
	v_mov_b32_e32 v62, 0
	v_mov_b32_e32 v63, 0
	v_mov_b32_e32 v64, 0
	v_mov_b32_e32 v65, 0
	v_mov_b32_e32 v56, 0
	v_mov_b32_e32 v57, 0
	s_and_saveexec_b64 s[0:1], s[44:45]
	s_cbranch_execz .LBB0_429
	v_lshl_add_u64 v[56:57], v[70:71], 0, v[54:55]
	v_mov_b32_e32 v76, v178
	v_mov_b32_e32 v77, v179
	v_mov_b32_e32 v78, v180
	v_mov_b32_e32 v79, v181
	v_lshlrev_b32_e32 v74, 16, v76
	v_and_b32_e32 v75, 0xffff0000, v76
	v_lshlrev_b32_e32 v62, 16, v77
	v_and_b32_e32 v63, 0xffff0000, v77
	v_lshlrev_b32_e32 v64, 16, v78
	v_and_b32_e32 v65, 0xffff0000, v78
	v_lshlrev_b32_e32 v56, 16, v79
	v_and_b32_e32 v57, 0xffff0000, v79
.LBB0_429:
	s_or_b64 exec, exec, s[0:1]
	v_lshlrev_b32_e32 v80, 16, v0
	v_and_b32_e32 v81, 0xffff0000, v0
	v_lshlrev_b32_e32 v82, 16, v1
	v_and_b32_e32 v83, 0xffff0000, v1
	v_lshlrev_b32_e32 v84, 16, v2
	v_and_b32_e32 v85, 0xffff0000, v2
	v_lshlrev_b32_e32 v86, 16, v3
	v_and_b32_e32 v87, 0xffff0000, v3
	v_mov_b32_e32 v0, v204
	v_mov_b32_e32 v1, v205
	v_mov_b32_e32 v2, v206
	v_mov_b32_e32 v3, v207
	v_mov_b32_e32 v76, v208
	v_mov_b32_e32 v77, v209
	v_mov_b32_e32 v78, v210
	v_mov_b32_e32 v79, v211
	v_pk_add_f32 v[64:65], v[64:65], v[84:85] neg_lo:[0,1] neg_hi:[0,1]
	v_mov_b64_e32 v[68:69], s[12:13]
	v_pk_add_f32 v[74:75], v[74:75], v[80:81] neg_lo:[0,1] neg_hi:[0,1]
	v_mad_i64_i32 v[68:69], s[0:1], v60, s37, v[68:69]
	v_mov_b32_e32 v59, 0
	v_pk_fma_f32 v[64:65], v[0:1], v[64:65], v[84:85]
	v_pk_add_f32 v[0:1], v[62:63], v[82:83] neg_lo:[0,1] neg_hi:[0,1]
	v_pk_fma_f32 v[74:75], v[76:77], v[74:75], v[80:81]
	v_pk_fma_f32 v[62:63], v[78:79], v[0:1], v[82:83]
	v_pk_add_f32 v[0:1], v[56:57], v[86:87] neg_lo:[0,1] neg_hi:[0,1]
	s_nop 0
	v_pk_fma_f32 v[56:57], v[2:3], v[0:1], v[86:87]
	v_cvt_pk_bf16_f32 v0, v74, v75
	v_cvt_pk_bf16_f32 v1, v62, v63
	v_cvt_pk_bf16_f32 v2, v64, v65
	v_cvt_pk_bf16_f32 v3, v56, v57
	v_lshl_add_u64 v[56:57], v[68:69], 0, v[54:55]
	global_store_dwordx4 v[56:57], v[0:3], off
	v_mov_b32_e32 v62, 0
	v_mov_b32_e32 v63, 0
	v_lshl_add_u64 v[0:1], v[72:73], 0, v[8:9]
	v_mov_b32_e32 v0, v158
	v_mov_b32_e32 v1, v159
	v_mov_b32_e32 v2, v160
	v_mov_b32_e32 v3, v161
	v_mov_b32_e32 v74, 0
	v_mov_b32_e32 v75, 0
	v_mov_b32_e32 v64, 0
	v_mov_b32_e32 v65, 0
	s_and_saveexec_b64 s[0:1], s[44:45]
	s_cbranch_execz .LBB0_431
	v_lshl_add_u64 v[58:59], v[70:71], 0, v[8:9]
	v_mov_b32_e32 v62, v182
	v_mov_b32_e32 v63, v183
	v_mov_b32_e32 v64, v184
	v_mov_b32_e32 v65, v185
	v_lshlrev_b32_e32 v58, 16, v62
	v_and_b32_e32 v59, 0xffff0000, v62
	v_lshlrev_b32_e32 v62, 16, v63
	v_and_b32_e32 v63, 0xffff0000, v63
	v_lshlrev_b32_e32 v74, 16, v64
	v_and_b32_e32 v75, 0xffff0000, v64
	v_lshlrev_b32_e32 v64, 16, v65
	v_and_b32_e32 v65, 0xffff0000, v65
.LBB0_431:
	s_or_b64 exec, exec, s[0:1]
	v_lshlrev_b32_e32 v80, 16, v0
	v_and_b32_e32 v81, 0xffff0000, v0
	v_lshlrev_b32_e32 v82, 16, v1
	v_and_b32_e32 v83, 0xffff0000, v1
	v_lshlrev_b32_e32 v84, 16, v2
	v_and_b32_e32 v85, 0xffff0000, v2
	v_lshlrev_b32_e32 v86, 16, v3
	v_and_b32_e32 v87, 0xffff0000, v3
	v_mov_b32_e32 v0, v212
	v_mov_b32_e32 v1, v213
	v_mov_b32_e32 v2, v214
	v_mov_b32_e32 v3, v215
	v_mov_b32_e32 v76, v216
	v_mov_b32_e32 v77, v217
	v_mov_b32_e32 v78, v218
	v_mov_b32_e32 v79, v219
	v_pk_add_f32 v[74:75], v[74:75], v[84:85] neg_lo:[0,1] neg_hi:[0,1]
	v_pk_add_f32 v[58:59], v[58:59], v[80:81] neg_lo:[0,1] neg_hi:[0,1]
	v_pk_fma_f32 v[74:75], v[0:1], v[74:75], v[84:85]
	v_pk_add_f32 v[0:1], v[62:63], v[82:83] neg_lo:[0,1] neg_hi:[0,1]
	v_pk_fma_f32 v[58:59], v[76:77], v[58:59], v[80:81]
	v_pk_fma_f32 v[62:63], v[78:79], v[0:1], v[82:83]
	v_pk_add_f32 v[0:1], v[64:65], v[86:87] neg_lo:[0,1] neg_hi:[0,1]
	v_mov_b32_e32 v78, 0
	v_pk_fma_f32 v[64:65], v[2:3], v[0:1], v[86:87]
	v_cvt_pk_bf16_f32 v0, v58, v59
	v_cvt_pk_bf16_f32 v1, v62, v63
	v_cvt_pk_bf16_f32 v2, v74, v75
	v_cvt_pk_bf16_f32 v3, v64, v65
	v_lshlrev_b32_e32 v62, 1, v36
	v_mov_b32_e32 v63, v9
	global_store_dwordx4 v[56:57], v[0:3], off offset:1024
	v_mov_b32_e32 v58, 0
	v_mov_b32_e32 v74, 0
	v_lshl_add_u64 v[0:1], v[72:73], 0, v[62:63]
	v_mov_b32_e32 v0, v162
	v_mov_b32_e32 v1, v163
	v_mov_b32_e32 v2, v164
	v_mov_b32_e32 v3, v165
	v_mov_b32_e32 v75, 0
	v_mov_b32_e32 v64, 0
	v_mov_b32_e32 v65, 0
	v_mov_b32_e32 v79, 0
	v_mov_b32_e32 v76, 0
	v_mov_b32_e32 v77, 0
	s_and_saveexec_b64 s[0:1], s[44:45]
	s_cbranch_execz .LBB0_433
	v_lshl_add_u64 v[64:65], v[70:71], 0, v[62:63]
	v_mov_b32_e32 v78, v188
	v_mov_b32_e32 v79, v189
	v_mov_b32_e32 v80, v190
	v_mov_b32_e32 v81, v191
	v_lshlrev_b32_e32 v74, 16, v78
	v_and_b32_e32 v75, 0xffff0000, v78
	v_lshlrev_b32_e32 v64, 16, v79
	v_and_b32_e32 v65, 0xffff0000, v79
	v_lshlrev_b32_e32 v78, 16, v80
	v_and_b32_e32 v79, 0xffff0000, v80
	v_lshlrev_b32_e32 v76, 16, v81
	v_and_b32_e32 v77, 0xffff0000, v81
; __global__ void __launch_bounds__(NTHREADS, 2) fwd_megakernel(Args args) {
;     ...
;             for (int it = 0; it < 6; ++it) {
;                 const int c8 = (it * 64 + lane) * 8;
;                 float cur[8], prv[8], o[8];
;                 unpack8(*(const u32x4*)(pr + C_CR + c8), cur);
;                 if (t > 0) unpack8(*(const u32x4*)(pr - NP + C_CR + c8), prv);
;                 else {
; #pragma unroll
;                     for (int i = 0; i < 8; ++i) prv[i] = 0.f;
;                 }
;                 const float* mp = mu + (size_t)l * 3200 + c8;
;                 const f32x4 m0 = *(const f32x4*)mp, m1 = *(const f32x4*)(mp + 4);
; #pragma unroll
;                 for (int i = 0; i < 4; ++i) { o[i] = cur[i] + (prv[i] - cur[i]) * m0[i]; o[4 + i] = cur[4 + i] + (prv[4 + i] - cur[4 + i]) * m1[i]; }
;                 *(u32x4*)(CRKV + (size_t)r * 3072 + c8) = pack8(o);
;             }
.LBB0_433:
	s_or_b64 exec, exec, s[0:1]
	v_lshlrev_b32_e32 v84, 16, v0
	v_and_b32_e32 v85, 0xffff0000, v0
	v_lshlrev_b32_e32 v86, 16, v1
	v_and_b32_e32 v87, 0xffff0000, v1
	v_lshlrev_b32_e32 v88, 16, v2
	v_and_b32_e32 v89, 0xffff0000, v2
	v_lshlrev_b32_e32 v90, 16, v3
	v_and_b32_e32 v91, 0xffff0000, v3
	v_mov_b32_e32 v0, v220
	v_mov_b32_e32 v1, v221
	v_mov_b32_e32 v2, v222
	v_mov_b32_e32 v3, v223
	v_mov_b32_e32 v80, v96
	v_mov_b32_e32 v81, v97
	v_mov_b32_e32 v82, v98
	v_mov_b32_e32 v83, v99
	v_pk_add_f32 v[78:79], v[78:79], v[88:89] neg_lo:[0,1] neg_hi:[0,1]
	v_pk_add_f32 v[74:75], v[74:75], v[84:85] neg_lo:[0,1] neg_hi:[0,1]
	v_mov_b32_e32 v59, 0
	v_pk_fma_f32 v[78:79], v[0:1], v[78:79], v[88:89]
	v_pk_add_f32 v[0:1], v[64:65], v[86:87] neg_lo:[0,1] neg_hi:[0,1]
	v_pk_fma_f32 v[74:75], v[80:81], v[74:75], v[84:85]
	v_pk_fma_f32 v[64:65], v[82:83], v[0:1], v[86:87]
	v_pk_add_f32 v[0:1], v[76:77], v[90:91] neg_lo:[0,1] neg_hi:[0,1]
	s_nop 0
	v_pk_fma_f32 v[76:77], v[2:3], v[0:1], v[90:91]
	v_cvt_pk_bf16_f32 v0, v74, v75
	v_cvt_pk_bf16_f32 v1, v64, v65
	v_cvt_pk_bf16_f32 v2, v78, v79
	v_cvt_pk_bf16_f32 v3, v76, v77
	v_lshlrev_b32_e32 v64, 1, v40
	v_mov_b32_e32 v65, v9
	global_store_dwordx4 v[56:57], v[0:3], off offset:2048
	v_mov_b32_e32 v74, 0
	v_mov_b32_e32 v75, 0
	v_lshl_add_u64 v[0:1], v[72:73], 0, v[64:65]
	v_mov_b32_e32 v0, v166
	v_mov_b32_e32 v1, v167
	v_mov_b32_e32 v2, v168
	v_mov_b32_e32 v3, v169
	v_mov_b32_e32 v78, 0
	v_mov_b32_e32 v79, 0
	v_mov_b32_e32 v76, 0
	v_mov_b32_e32 v77, 0
	s_and_saveexec_b64 s[0:1], s[44:45]
	s_cbranch_execz .LBB0_435
	v_lshl_add_u64 v[58:59], v[70:71], 0, v[64:65]
	v_mov_b32_e32 v74, v192
	v_mov_b32_e32 v75, v193
	v_mov_b32_e32 v76, v194
	v_mov_b32_e32 v77, v195
	v_lshlrev_b32_e32 v58, 16, v74
	v_and_b32_e32 v59, 0xffff0000, v74
	v_lshlrev_b32_e32 v74, 16, v75
	v_and_b32_e32 v75, 0xffff0000, v75
	v_lshlrev_b32_e32 v78, 16, v76
	v_and_b32_e32 v79, 0xffff0000, v76
	v_lshlrev_b32_e32 v76, 16, v77
	v_and_b32_e32 v77, 0xffff0000, v77
.LBB0_435:
	s_or_b64 exec, exec, s[0:1]
	v_lshlrev_b32_e32 v84, 16, v0
	v_and_b32_e32 v85, 0xffff0000, v0
	v_lshlrev_b32_e32 v86, 16, v1
	v_and_b32_e32 v87, 0xffff0000, v1
	v_lshlrev_b32_e32 v88, 16, v2
	v_and_b32_e32 v89, 0xffff0000, v2
	v_lshlrev_b32_e32 v90, 16, v3
	v_and_b32_e32 v91, 0xffff0000, v3
	v_mov_b32_e32 v0, v102
	v_mov_b32_e32 v1, v103
	v_mov_b32_e32 v2, v104
	v_mov_b32_e32 v3, v105
	v_mov_b32_e32 v80, v106
	v_mov_b32_e32 v81, v107
	v_mov_b32_e32 v82, v108
	v_mov_b32_e32 v83, v109
	v_pk_add_f32 v[78:79], v[78:79], v[88:89] neg_lo:[0,1] neg_hi:[0,1]
	v_pk_add_f32 v[58:59], v[58:59], v[84:85] neg_lo:[0,1] neg_hi:[0,1]
	v_pk_fma_f32 v[78:79], v[0:1], v[78:79], v[88:89]
	v_pk_add_f32 v[0:1], v[74:75], v[86:87] neg_lo:[0,1] neg_hi:[0,1]
	v_pk_fma_f32 v[58:59], v[80:81], v[58:59], v[84:85]
	v_pk_fma_f32 v[74:75], v[82:83], v[0:1], v[86:87]
	v_pk_add_f32 v[0:1], v[76:77], v[90:91] neg_lo:[0,1] neg_hi:[0,1]
	v_mov_b32_e32 v80, 0
	v_pk_fma_f32 v[76:77], v[2:3], v[0:1], v[90:91]
	v_cvt_pk_bf16_f32 v0, v58, v59
	v_cvt_pk_bf16_f32 v1, v74, v75
	v_cvt_pk_bf16_f32 v2, v78, v79
	v_cvt_pk_bf16_f32 v3, v76, v77
	global_store_dwordx4 v[56:57], v[0:3], off offset:3072
	v_lshlrev_b32_e32 v56, 1, v44
	v_mov_b32_e32 v57, v9
	v_lshl_add_u64 v[0:1], v[72:73], 0, v[56:57]
	v_mov_b32_e32 v0, v170
	v_mov_b32_e32 v1, v171
	v_mov_b32_e32 v2, v172
	v_mov_b32_e32 v3, v173
	v_mov_b32_e32 v74, 0
	v_mov_b32_e32 v76, 0
	v_mov_b32_e32 v77, 0
	v_mov_b32_e32 v58, 0
	v_mov_b32_e32 v59, 0
	v_mov_b32_e32 v81, 0
	v_mov_b32_e32 v78, 0
	v_mov_b32_e32 v79, 0
	s_and_saveexec_b64 s[0:1], s[44:45]
	s_cbranch_execz .LBB0_437
	v_lshl_add_u64 v[58:59], v[70:71], 0, v[56:57]
	v_mov_b32_e32 v80, v196
	v_mov_b32_e32 v81, v197
	v_mov_b32_e32 v82, v198
	v_mov_b32_e32 v83, v199
	v_lshlrev_b32_e32 v76, 16, v80
	v_and_b32_e32 v77, 0xffff0000, v80
	v_lshlrev_b32_e32 v58, 16, v81
	v_and_b32_e32 v59, 0xffff0000, v81
	v_lshlrev_b32_e32 v80, 16, v82
	v_and_b32_e32 v81, 0xffff0000, v82
	v_lshlrev_b32_e32 v78, 16, v83
	v_and_b32_e32 v79, 0xffff0000, v83
; __global__ void __launch_bounds__(NTHREADS, 2) fwd_megakernel(Args args) {
;     ...
;             for (int it = 0; it < 6; ++it) {
;                 const int c8 = (it * 64 + lane) * 8;
;                 float cur[8], prv[8], o[8];
;                 unpack8(*(const u32x4*)(pr + C_CR + c8), cur);
;                 if (t > 0) unpack8(*(const u32x4*)(pr - NP + C_CR + c8), prv);
;                 else {
; #pragma unroll
;                     for (int i = 0; i < 8; ++i) prv[i] = 0.f;
;                 }
;                 const float* mp = mu + (size_t)l * 3200 + c8;
;                 const f32x4 m0 = *(const f32x4*)mp, m1 = *(const f32x4*)(mp + 4);
; #pragma unroll
;                 for (int i = 0; i < 4; ++i) { o[i] = cur[i] + (prv[i] - cur[i]) * m0[i]; o[4 + i] = cur[4 + i] + (prv[4 + i] - cur[4 + i]) * m1[i]; }
;                 *(u32x4*)(CRKV + (size_t)r * 3072 + c8) = pack8(o);
;             }
;             if (lane < 16) {
;                 const int c8 = lane * 8;
;                 float cur[8], prv[8], o[8];
;                 unpack8(*(const u32x4*)(pr + C_WD + c8), cur);
;                 if (t > 0) unpack8(*(const u32x4*)(pr - NP + C_WD + c8), prv);
.LBB0_437:
	s_or_b64 exec, exec, s[0:1]
	v_lshlrev_b32_e32 v86, 16, v0
	v_and_b32_e32 v87, 0xffff0000, v0
	v_lshlrev_b32_e32 v88, 16, v1
	v_and_b32_e32 v89, 0xffff0000, v1
	v_lshlrev_b32_e32 v90, 16, v2
	v_and_b32_e32 v91, 0xffff0000, v2
	v_lshlrev_b32_e32 v92, 16, v3
	v_and_b32_e32 v93, 0xffff0000, v3
	v_mov_b32_e32 v0, v110
	v_mov_b32_e32 v1, v111
	v_mov_b32_e32 v2, v112
	v_mov_b32_e32 v3, v113
	v_mov_b32_e32 v82, v116
	v_mov_b32_e32 v83, v117
	v_mov_b32_e32 v84, v118
	v_mov_b32_e32 v85, v119
	v_pk_add_f32 v[80:81], v[80:81], v[90:91] neg_lo:[0,1] neg_hi:[0,1]
	v_pk_add_f32 v[76:77], v[76:77], v[86:87] neg_lo:[0,1] neg_hi:[0,1]
	v_mov_b32_e32 v75, 0
	v_pk_fma_f32 v[80:81], v[0:1], v[80:81], v[90:91]
	v_pk_add_f32 v[0:1], v[58:59], v[88:89] neg_lo:[0,1] neg_hi:[0,1]
	v_pk_fma_f32 v[76:77], v[82:83], v[76:77], v[86:87]
	v_pk_fma_f32 v[58:59], v[84:85], v[0:1], v[88:89]
	v_pk_add_f32 v[0:1], v[78:79], v[92:93] neg_lo:[0,1] neg_hi:[0,1]
	s_nop 0
	v_pk_fma_f32 v[78:79], v[2:3], v[0:1], v[92:93]
	v_cvt_pk_bf16_f32 v0, v76, v77
	v_cvt_pk_bf16_f32 v1, v58, v59
	v_cvt_pk_bf16_f32 v2, v80, v81
	v_cvt_pk_bf16_f32 v3, v78, v79
	v_lshl_add_u64 v[58:59], v[68:69], 0, v[56:57]
	global_store_dwordx4 v[58:59], v[0:3], off
	v_lshlrev_b32_e32 v58, 1, v48
	v_mov_b32_e32 v59, v9
	v_lshl_add_u64 v[0:1], v[72:73], 0, v[58:59]
	v_mov_b32_e32 v0, v174
	v_mov_b32_e32 v1, v175
	v_mov_b32_e32 v2, v176
	v_mov_b32_e32 v3, v177
	v_mov_b32_e32 v72, 0
	v_mov_b32_e32 v73, 0
	v_mov_b32_e32 v78, 0
	v_mov_b32_e32 v79, 0
	v_mov_b32_e32 v76, 0
	v_mov_b32_e32 v77, 0
	s_and_saveexec_b64 s[0:1], s[44:45]
	s_cbranch_execz .LBB0_439
	v_lshl_add_u64 v[70:71], v[70:71], 0, v[58:59]
	v_mov_b32_e32 v78, v200
	v_mov_b32_e32 v79, v201
	v_mov_b32_e32 v80, v202
	v_mov_b32_e32 v81, v203
	v_lshlrev_b32_e32 v74, 16, v78
	v_and_b32_e32 v75, 0xffff0000, v78
	v_lshlrev_b32_e32 v72, 16, v79
	v_and_b32_e32 v73, 0xffff0000, v79
	v_lshlrev_b32_e32 v78, 16, v80
	v_and_b32_e32 v79, 0xffff0000, v80
	v_lshlrev_b32_e32 v76, 16, v81
	v_and_b32_e32 v77, 0xffff0000, v81
.LBB0_439:
	s_or_b64 exec, exec, s[0:1]
	v_lshlrev_b32_e32 v70, 16, v0
	v_and_b32_e32 v71, 0xffff0000, v0
	v_lshlrev_b32_e32 v84, 16, v1
	v_and_b32_e32 v85, 0xffff0000, v1
	v_lshlrev_b32_e32 v86, 16, v2
	v_and_b32_e32 v87, 0xffff0000, v2
	v_lshlrev_b32_e32 v88, 16, v3
	v_and_b32_e32 v89, 0xffff0000, v3
	v_mov_b32_e32 v0, v120
	v_mov_b32_e32 v1, v121
	v_mov_b32_e32 v2, v122
	v_mov_b32_e32 v3, v123
	v_mov_b32_e32 v80, v136
	v_mov_b32_e32 v81, v137
	v_mov_b32_e32 v82, v138
	v_mov_b32_e32 v83, v139
	v_pk_add_f32 v[74:75], v[74:75], v[70:71] neg_lo:[0,1] neg_hi:[0,1]
	v_lshl_add_u64 v[68:69], v[68:69], 0, v[58:59]
	s_mov_b64 s[0:1], 0
	v_pk_fma_f32 v[70:71], v[80:81], v[74:75], v[70:71]
	v_pk_add_f32 v[74:75], v[78:79], v[86:87] neg_lo:[0,1] neg_hi:[0,1]
	s_nop 0
	v_pk_fma_f32 v[74:75], v[0:1], v[74:75], v[86:87]
	v_pk_add_f32 v[0:1], v[72:73], v[84:85] neg_lo:[0,1] neg_hi:[0,1]
	s_nop 0
	v_pk_fma_f32 v[72:73], v[82:83], v[0:1], v[84:85]
	v_pk_add_f32 v[0:1], v[76:77], v[88:89] neg_lo:[0,1] neg_hi:[0,1]
	s_nop 0
	v_pk_fma_f32 v[76:77], v[2:3], v[0:1], v[88:89]
	v_cvt_pk_bf16_f32 v0, v70, v71
	v_cvt_pk_bf16_f32 v1, v72, v73
	v_cvt_pk_bf16_f32 v2, v74, v75
	v_cvt_pk_bf16_f32 v3, v76, v77
	global_store_dwordx4 v[68:69], v[0:3], off
	s_and_saveexec_b64 s[24:25], s[40:41]
	s_xor_b64 s[46:47], exec, s[24:25]
	s_and_b64 s[0:1], s[42:43], exec
	s_or_saveexec_b64 s[46:47], s[46:47]
	v_mov_b32_e32 v3, 0
	v_mov_b32_e32 v2, 0
	v_mov_b32_e32 v1, 0
	v_mov_b32_e32 v0, 0
	s_xor_b64 exec, exec, s[46:47]
	s_cbranch_execz .LBB0_479
	v_mov_b32_e32 v55, v9
	v_lshl_add_u64 v[74:75], v[66:67], 0, v[54:55]
	v_add_co_u32_e32 v0, vcc, 0x9000, v74
	v_mov_b32_e32 v66, 0
	s_nop 0
	v_addc_co_u32_e32 v1, vcc, 0, v75, vcc
	global_load_dwordx4 v[0:3], v[0:1], off
	v_mov_b32_e32 v67, v66
	v_mov_b32_e32 v68, v66
	v_mov_b32_e32 v69, v66
	v_mov_b32_e32 v72, v66
	v_mov_b32_e32 v73, v66
	v_mov_b32_e32 v70, v66
	v_mov_b32_e32 v71, v66
	s_and_saveexec_b64 s[48:49], s[44:45]
	s_cbranch_execz .LBB0_444
	global_load_dwordx4 v[72:75], v[74:75], off offset:-512
	s_waitcnt vmcnt(0)
	v_lshlrev_b32_e32 v70, 16, v72
	v_and_b32_e32 v71, 0xffff0000, v72
	v_lshlrev_b32_e32 v68, 16, v73
	v_and_b32_e32 v69, 0xffff0000, v73
	v_lshlrev_b32_e32 v72, 16, v74
	v_and_b32_e32 v73, 0xffff0000, v74
	v_lshlrev_b32_e32 v66, 16, v75
	v_and_b32_e32 v67, 0xffff0000, v75

; __device__ __forceinline__ float siluf_(float x) { return x * __builtin_amdgcn_rcpf(1.0f + __expf(-x)); }
; __global__ void __launch_bounds__(NTHREADS, 2) fwd_megakernel(Args args) {
;     ...
;         for (int r = gw; r < M; r += NGW) {
;             const int b = r / T, t = r - b * T;
;             const bf16_t* pr = PROJ + (size_t)r * NP;
; #pragma unroll
;             for (int it = 0; it < 2; ++it) {
;                 const int c8 = (it * 64 + lane) * 8;
;                 float o[8];
; #pragma unroll
;                 for (int i = 0; i < 8; ++i) o[i] = 0.f;
; #pragma unroll
;                 for (int j = 0; j < 4; ++j) {
;                     if (t - 3 + j >= 0) {
;                         float xv[8]; unpack8(*(const u32x4*)(pr - (size_t)(3 - j) * NP + C_BQ + c8), xv);
;                         const float* wp = mconv + ((size_t)l * 4 + j) * 1024 + c8;
;                         const f32x4 w0v = *(const f32x4*)wp, w1v = *(const f32x4*)(wp + 4);
; #pragma unroll
;                         for (int i = 0; i < 4; ++i) { o[i] += w0v[i] * xv[i]; o[4 + i] += w1v[i] * xv[4 + i]; }
;                     }
;                 }
;                 const float sc = (c8 < 512) ? 0.08838834764831845f : 1.0f;
; #pragma unroll
;                 for (int i = 0; i < 8; ++i) o[i] = siluf_(o[i]) * sc;
;                 *(u32x4*)(BQK + (size_t)r * 1024 + c8) = pack8(o);
;             }
;             if (lane < 8) {
;                 const float raw = IGFG[(size_t)r * 8 + lane];
;                 float o;
;                 if (lane < 4) o = raw + ig_b[l * 4 + lane];
;                 else { const float z = raw + fg_b[l * 4 + (lane - 4)]; o = fminf(z, 0.f) - __logf(1.0f + __expf(-fabsf(z))); }
;                 IL[(size_t)r * 8 + lane] = o;
;             }
; #pragma unroll
;             for (int it = 0; it < 6; ++it) {
;                 const int c8 = (it * 64 + lane) * 8;
;                 float cur[8], prv[8], o[8];
;                 unpack8(*(const u32x4*)(pr + C_CR + c8), cur);
;                 if (t > 0) unpack8(*(const u32x4*)(pr - NP + C_CR + c8), prv);
;                 else {
; #pragma unroll
;                     for (int i = 0; i < 8; ++i) prv[i] = 0.f;
;                 }
;                 const float* mp = mu + (size_t)l * 3200 + c8;
;                 const f32x4 m0 = *(const f32x4*)mp, m1 = *(const f32x4*)(mp + 4);
; #pragma unroll
.LBB0_481:
	s_or_b64 exec, exec, s[44:45]
	v_add_u32_e32 v66, s74, v60
	s_movk_i32 s0, 0x4020
	v_cmp_gt_i32_e32 vcc, s0, v66
	s_mov_b64 s[0:1], -1
	s_and_saveexec_b64 s[54:55], vcc
	s_cbranch_execz .LBB0_410
	v_mul_hi_i32 v0, v66, s14
	v_lshrrev_b32_e32 v1, 31, v0
	v_ashrrev_i32_e32 v0, 12, v0
	v_add_u32_e32 v0, v0, v1
	v_mul_i32_i24_e32 v0, 0x2010, v0
	v_sub_u32_e32 v5, v66, v0
	v_mov_b64_e32 v[0:1], s[78:79]
	v_mov_b32_e32 v72, 0
	v_mad_i64_i32 v[60:61], s[0:1], v66, s58, v[0:1]
	v_and_b32_e32 v100, 63, v226
	v_lshlrev_b32_e32 v100, 4, v100
	v_mov_b32_e32 v101, 0
	v_lshl_add_u64 v[224:225], v[60:61], 0, v[100:101]
	s_mov_b64 s[100:101], 0x4000
	v_lshl_add_u64 v[140:141], v[224:225], 0, s[100:101]
	global_load_dwordx4 v[154:157], v[140:141], off
	global_load_dwordx4 v[158:161], v[140:141], off offset:1024
	global_load_dwordx4 v[162:165], v[140:141], off offset:2048
	global_load_dwordx4 v[166:169], v[140:141], off offset:3072
	s_mov_b64 s[100:101], 0x5000
	v_lshl_add_u64 v[140:141], v[224:225], 0, s[100:101]
	global_load_dwordx4 v[170:173], v[140:141], off
	global_load_dwordx4 v[174:177], v[140:141], off offset:1024
	s_mov_b32 s100, 0xffffae00
	s_mov_b32 s101, -1
	v_lshl_add_u64 v[140:141], v[224:225], 0, s[100:101]
	global_load_dwordx4 v[178:181], v[140:141], off
	global_load_dwordx4 v[182:185], v[140:141], off offset:1024
	global_load_dwordx4 v[188:191], v[140:141], off offset:2048
	global_load_dwordx4 v[192:195], v[140:141], off offset:3072
	s_mov_b32 s100, 0xffffbe00
	s_mov_b32 s101, -1
	v_lshl_add_u64 v[140:141], v[224:225], 0, s[100:101]
	global_load_dwordx4 v[196:199], v[140:141], off
	global_load_dwordx4 v[200:203], v[140:141], off offset:1024
	global_load_dwordx4 v[204:207], v[16:17], off offset:16
	global_load_dwordx4 v[208:211], v[16:17], off
	global_load_dwordx4 v[212:215], v[16:17], off offset:2064
	global_load_dwordx4 v[216:219], v[16:17], off offset:2048
	global_load_dwordx4 v[220:223], v[38:39], off offset:16
	global_load_dwordx4 v[96:99], v[38:39], off
	global_load_dwordx4 v[102:105], v[42:43], off offset:16
	global_load_dwordx4 v[106:109], v[42:43], off
	global_load_dwordx4 v[110:113], v[46:47], off offset:16
	global_load_dwordx4 v[116:119], v[46:47], off
	global_load_dwordx4 v[120:123], v[50:51], off offset:16
	global_load_dwordx4 v[136:139], v[50:51], off
	v_cmp_lt_i32_e64 s[46:47], 2, v5
	v_mov_b32_e32 v73, 0
	v_mov_b32_e32 v68, 0
	v_mov_b32_e32 v69, v72
	v_mov_b32_e32 v2, v72
	v_mov_b32_e32 v3, v72
	v_mov_b32_e32 v0, v72
	v_mov_b32_e32 v1, v72
	v_mov_b32_e32 v70, v72
	v_mov_b32_e32 v71, v72
	s_and_saveexec_b64 s[0:1], s[46:47]
	s_cbranch_execnz .LBB0_558
	s_or_b64 exec, exec, s[0:1]
	v_cmp_lt_i32_e64 s[48:49], 1, v5
	s_and_saveexec_b64 s[0:1], s[48:49]
	s_cbranch_execnz .LBB0_559

; __global__ void __launch_bounds__(NTHREADS, 2) fwd_megakernel(Args args) {
;     ...
;             for (int it = 0; it < 6; ++it) {
;                 const int c8 = (it * 64 + lane) * 8;
;                 float cur[8], prv[8], o[8];
;                 unpack8(*(const u32x4*)(pr + C_CR + c8), cur);
;                 if (t > 0) unpack8(*(const u32x4*)(pr - NP + C_CR + c8), prv);
;                 else {
; #pragma unroll
;                     for (int i = 0; i < 8; ++i) prv[i] = 0.f;
;                 }
;                 const float* mp = mu + (size_t)l * 3200 + c8;
;                 const f32x4 m0 = *(const f32x4*)mp, m1 = *(const f32x4*)(mp + 4);
; #pragma unroll
;                 for (int i = 0; i < 4; ++i) { o[i] = cur[i] + (prv[i] - cur[i]) * m0[i]; o[4 + i] = cur[4 + i] + (prv[4 + i] - cur[4 + i]) * m1[i]; }
;                 *(u32x4*)(CRKV + (size_t)r * 3072 + c8) = pack8(o);
;             }
.LBB0_498:
	s_or_b64 exec, exec, s[46:47]
	s_mov_b64 s[0:1], 0x4000
	v_lshl_add_u64 v[72:73], v[60:61], 0, s[0:1]
	v_mov_b32_e32 v55, v9
	v_lshl_add_u64 v[0:1], v[72:73], 0, v[54:55]
	s_waitcnt vmcnt(0)
	v_mov_b32_e32 v0, v154
	v_mov_b32_e32 v1, v155
	v_mov_b32_e32 v2, v156
	v_mov_b32_e32 v3, v157
	s_movk_i32 s0, 0xae00
	s_mov_b32 s1, -1
	v_lshl_add_u64 v[70:71], v[60:61], 0, s[0:1]
	v_mov_b32_e32 v76, 0
	v_mov_b32_e32 v82, 0
	v_mov_b32_e32 v83, 0
	v_mov_b32_e32 v78, 0
	v_mov_b32_e32 v79, 0
	v_mov_b32_e32 v80, 0
	v_mov_b32_e32 v81, 0
	v_mov_b32_e32 v74, 0
	v_mov_b32_e32 v75, 0
	s_and_saveexec_b64 s[0:1], s[44:45]
	s_cbranch_execz .LBB0_500
	v_lshl_add_u64 v[68:69], v[70:71], 0, v[54:55]
	v_mov_b32_e32 v84, v178
	v_mov_b32_e32 v85, v179
	v_mov_b32_e32 v86, v180
	v_mov_b32_e32 v87, v181
	v_lshlrev_b32_e32 v82, 16, v84
	v_and_b32_e32 v83, 0xffff0000, v84
	v_lshlrev_b32_e32 v78, 16, v85
	v_and_b32_e32 v79, 0xffff0000, v85
	v_lshlrev_b32_e32 v80, 16, v86
	v_and_b32_e32 v81, 0xffff0000, v86
	v_lshlrev_b32_e32 v74, 16, v87
	v_and_b32_e32 v75, 0xffff0000, v87
.LBB0_500:
	s_or_b64 exec, exec, s[0:1]
	v_lshlrev_b32_e32 v88, 16, v0
	v_and_b32_e32 v89, 0xffff0000, v0
	v_lshlrev_b32_e32 v90, 16, v1
	v_and_b32_e32 v91, 0xffff0000, v1
	v_lshlrev_b32_e32 v92, 16, v2
	v_and_b32_e32 v93, 0xffff0000, v2
	v_lshlrev_b32_e32 v94, 16, v3
	v_and_b32_e32 v95, 0xffff0000, v3
	v_mov_b32_e32 v0, v204
	v_mov_b32_e32 v1, v205
	v_mov_b32_e32 v2, v206
	v_mov_b32_e32 v3, v207
	v_mov_b32_e32 v84, v208
	v_mov_b32_e32 v85, v209
	v_mov_b32_e32 v86, v210
	v_mov_b32_e32 v87, v211
	v_pk_add_f32 v[80:81], v[80:81], v[92:93] neg_lo:[0,1] neg_hi:[0,1]
	v_mov_b64_e32 v[68:69], s[12:13]
	v_pk_add_f32 v[82:83], v[82:83], v[88:89] neg_lo:[0,1] neg_hi:[0,1]
	v_mad_i64_i32 v[68:69], s[0:1], v66, s37, v[68:69]
	v_mov_b32_e32 v77, 0
	v_pk_fma_f32 v[80:81], v[0:1], v[80:81], v[92:93]
	v_pk_add_f32 v[0:1], v[78:79], v[90:91] neg_lo:[0,1] neg_hi:[0,1]
	v_pk_fma_f32 v[82:83], v[84:85], v[82:83], v[88:89]
	v_pk_fma_f32 v[78:79], v[86:87], v[0:1], v[90:91]
	v_pk_add_f32 v[0:1], v[74:75], v[94:95] neg_lo:[0,1] neg_hi:[0,1]
	s_nop 0
	v_pk_fma_f32 v[74:75], v[2:3], v[0:1], v[94:95]
	v_cvt_pk_bf16_f32 v0, v82, v83
	v_cvt_pk_bf16_f32 v1, v78, v79
	v_cvt_pk_bf16_f32 v2, v80, v81
	v_cvt_pk_bf16_f32 v3, v74, v75
	v_lshl_add_u64 v[74:75], v[68:69], 0, v[54:55]
	global_store_dwordx4 v[74:75], v[0:3], off
	v_mov_b32_e32 v78, 0
	v_mov_b32_e32 v79, 0
	v_lshl_add_u64 v[0:1], v[72:73], 0, v[8:9]
	v_mov_b32_e32 v0, v158
	v_mov_b32_e32 v1, v159
	v_mov_b32_e32 v2, v160
	v_mov_b32_e32 v3, v161
	v_mov_b32_e32 v82, 0
	v_mov_b32_e32 v83, 0
	v_mov_b32_e32 v80, 0
	v_mov_b32_e32 v81, 0
	s_and_saveexec_b64 s[0:1], s[44:45]
	s_cbranch_execz .LBB0_502
	v_lshl_add_u64 v[76:77], v[70:71], 0, v[8:9]
	v_mov_b32_e32 v78, v182
	v_mov_b32_e32 v79, v183
	v_mov_b32_e32 v80, v184
	v_mov_b32_e32 v81, v185
	v_lshlrev_b32_e32 v76, 16, v78
	v_and_b32_e32 v77, 0xffff0000, v78
	v_lshlrev_b32_e32 v78, 16, v79
	v_and_b32_e32 v79, 0xffff0000, v79
	v_lshlrev_b32_e32 v82, 16, v80
	v_and_b32_e32 v83, 0xffff0000, v80
	v_lshlrev_b32_e32 v80, 16, v81
	v_and_b32_e32 v81, 0xffff0000, v81
.LBB0_502:
	s_or_b64 exec, exec, s[0:1]
	v_lshlrev_b32_e32 v88, 16, v0
	v_and_b32_e32 v89, 0xffff0000, v0
	v_lshlrev_b32_e32 v90, 16, v1
	v_and_b32_e32 v91, 0xffff0000, v1
	v_lshlrev_b32_e32 v92, 16, v2
	v_and_b32_e32 v93, 0xffff0000, v2
	v_lshlrev_b32_e32 v94, 16, v3
	v_and_b32_e32 v95, 0xffff0000, v3
	v_mov_b32_e32 v0, v212
	v_mov_b32_e32 v1, v213
	v_mov_b32_e32 v2, v214
	v_mov_b32_e32 v3, v215
	v_mov_b32_e32 v84, v216
	v_mov_b32_e32 v85, v217
	v_mov_b32_e32 v86, v218
	v_mov_b32_e32 v87, v219
	v_pk_add_f32 v[82:83], v[82:83], v[92:93] neg_lo:[0,1] neg_hi:[0,1]
	v_pk_add_f32 v[76:77], v[76:77], v[88:89] neg_lo:[0,1] neg_hi:[0,1]
	v_mov_b32_e32 v63, v9
	v_pk_fma_f32 v[82:83], v[0:1], v[82:83], v[92:93]
	v_pk_add_f32 v[0:1], v[78:79], v[90:91] neg_lo:[0,1] neg_hi:[0,1]
	v_pk_fma_f32 v[76:77], v[84:85], v[76:77], v[88:89]
	v_pk_fma_f32 v[78:79], v[86:87], v[0:1], v[90:91]
	v_pk_add_f32 v[0:1], v[80:81], v[94:95] neg_lo:[0,1] neg_hi:[0,1]
	v_mov_b32_e32 v84, 0
	v_pk_fma_f32 v[80:81], v[2:3], v[0:1], v[94:95]
	v_cvt_pk_bf16_f32 v0, v76, v77
	v_cvt_pk_bf16_f32 v1, v78, v79
	v_cvt_pk_bf16_f32 v2, v82, v83
	v_cvt_pk_bf16_f32 v3, v80, v81
	global_store_dwordx4 v[74:75], v[0:3], off offset:1024
	v_mov_b32_e32 v76, 0
	v_mov_b32_e32 v80, 0
	v_lshl_add_u64 v[0:1], v[72:73], 0, v[62:63]
	v_mov_b32_e32 v0, v162
	v_mov_b32_e32 v1, v163
	v_mov_b32_e32 v2, v164
	v_mov_b32_e32 v3, v165
	v_mov_b32_e32 v81, 0
	v_mov_b32_e32 v78, 0
	v_mov_b32_e32 v79, 0
	v_mov_b32_e32 v85, 0
	v_mov_b32_e32 v82, 0
	v_mov_b32_e32 v83, 0
	s_and_saveexec_b64 s[0:1], s[44:45]
	s_cbranch_execz .LBB0_504
	v_lshl_add_u64 v[62:63], v[70:71], 0, v[62:63]
	v_mov_b32_e32 v84, v188
	v_mov_b32_e32 v85, v189
	v_mov_b32_e32 v86, v190
	v_mov_b32_e32 v87, v191
	v_lshlrev_b32_e32 v80, 16, v84
	v_and_b32_e32 v81, 0xffff0000, v84
	v_lshlrev_b32_e32 v78, 16, v85
	v_and_b32_e32 v79, 0xffff0000, v85
	v_lshlrev_b32_e32 v84, 16, v86
	v_and_b32_e32 v85, 0xffff0000, v86
	v_lshlrev_b32_e32 v82, 16, v87
	v_and_b32_e32 v83, 0xffff0000, v87
; __global__ void __launch_bounds__(NTHREADS, 2) fwd_megakernel(Args args) {
;     ...
;             for (int it = 0; it < 6; ++it) {
;                 const int c8 = (it * 64 + lane) * 8;
;                 float cur[8], prv[8], o[8];
;                 unpack8(*(const u32x4*)(pr + C_CR + c8), cur);
;                 if (t > 0) unpack8(*(const u32x4*)(pr - NP + C_CR + c8), prv);
;                 else {
; #pragma unroll
;                     for (int i = 0; i < 8; ++i) prv[i] = 0.f;
;                 }
;                 const float* mp = mu + (size_t)l * 3200 + c8;
;                 const f32x4 m0 = *(const f32x4*)mp, m1 = *(const f32x4*)(mp + 4);
; #pragma unroll
;                 for (int i = 0; i < 4; ++i) { o[i] = cur[i] + (prv[i] - cur[i]) * m0[i]; o[4 + i] = cur[4 + i] + (prv[4 + i] - cur[4 + i]) * m1[i]; }
;                 *(u32x4*)(CRKV + (size_t)r * 3072 + c8) = pack8(o);
;             }
.LBB0_504:
	s_or_b64 exec, exec, s[0:1]
	v_lshlrev_b32_e32 v62, 16, v0
	v_and_b32_e32 v63, 0xffff0000, v0
	v_lshlrev_b32_e32 v90, 16, v1
	v_and_b32_e32 v91, 0xffff0000, v1
	v_lshlrev_b32_e32 v92, 16, v2
	v_and_b32_e32 v93, 0xffff0000, v2
	v_lshlrev_b32_e32 v94, 16, v3
	v_and_b32_e32 v95, 0xffff0000, v3
	v_mov_b32_e32 v0, v220
	v_mov_b32_e32 v1, v221
	v_mov_b32_e32 v2, v222
	v_mov_b32_e32 v3, v223
	v_mov_b32_e32 v86, v96
	v_mov_b32_e32 v87, v97
	v_mov_b32_e32 v88, v98
	v_mov_b32_e32 v89, v99
	v_pk_add_f32 v[80:81], v[80:81], v[62:63] neg_lo:[0,1] neg_hi:[0,1]
	v_mov_b32_e32 v65, v9
	v_mov_b32_e32 v77, 0
	v_pk_fma_f32 v[62:63], v[86:87], v[80:81], v[62:63]
	v_pk_add_f32 v[80:81], v[84:85], v[92:93] neg_lo:[0,1] neg_hi:[0,1]
	s_nop 0
	v_pk_fma_f32 v[80:81], v[0:1], v[80:81], v[92:93]
	v_pk_add_f32 v[0:1], v[78:79], v[90:91] neg_lo:[0,1] neg_hi:[0,1]
	s_nop 0
	v_pk_fma_f32 v[78:79], v[88:89], v[0:1], v[90:91]
	v_pk_add_f32 v[0:1], v[82:83], v[94:95] neg_lo:[0,1] neg_hi:[0,1]
	s_nop 0
	v_pk_fma_f32 v[82:83], v[2:3], v[0:1], v[94:95]
	v_cvt_pk_bf16_f32 v0, v62, v63
	v_cvt_pk_bf16_f32 v1, v78, v79
	v_cvt_pk_bf16_f32 v2, v80, v81
	v_cvt_pk_bf16_f32 v3, v82, v83
	global_store_dwordx4 v[74:75], v[0:3], off offset:2048
	v_mov_b32_e32 v62, 0
	v_mov_b32_e32 v63, 0
	v_lshl_add_u64 v[0:1], v[72:73], 0, v[64:65]
	v_mov_b32_e32 v0, v166
	v_mov_b32_e32 v1, v167
	v_mov_b32_e32 v2, v168
	v_mov_b32_e32 v3, v169
	v_mov_b32_e32 v80, 0
	v_mov_b32_e32 v81, 0
	v_mov_b32_e32 v78, 0
	v_mov_b32_e32 v79, 0
	s_and_saveexec_b64 s[0:1], s[44:45]
	s_cbranch_execz .LBB0_506
	v_lshl_add_u64 v[62:63], v[70:71], 0, v[64:65]
	v_mov_b32_e32 v62, v192
	v_mov_b32_e32 v63, v193
	v_mov_b32_e32 v64, v194
	v_mov_b32_e32 v65, v195
	v_lshlrev_b32_e32 v76, 16, v62
	v_and_b32_e32 v77, 0xffff0000, v62
	v_lshlrev_b32_e32 v62, 16, v63
	v_and_b32_e32 v63, 0xffff0000, v63
	v_lshlrev_b32_e32 v80, 16, v64
	v_and_b32_e32 v81, 0xffff0000, v64
	v_lshlrev_b32_e32 v78, 16, v65
	v_and_b32_e32 v79, 0xffff0000, v65
.LBB0_506:
	s_or_b64 exec, exec, s[0:1]
	v_lshlrev_b32_e32 v64, 16, v0
	v_and_b32_e32 v65, 0xffff0000, v0
	v_lshlrev_b32_e32 v86, 16, v1
	v_and_b32_e32 v87, 0xffff0000, v1
	v_lshlrev_b32_e32 v88, 16, v2
	v_and_b32_e32 v89, 0xffff0000, v2
	v_lshlrev_b32_e32 v90, 16, v3
	v_and_b32_e32 v91, 0xffff0000, v3
	v_mov_b32_e32 v0, v102
	v_mov_b32_e32 v1, v103
	v_mov_b32_e32 v2, v104
	v_mov_b32_e32 v3, v105
	v_mov_b32_e32 v82, v106
	v_mov_b32_e32 v83, v107
	v_mov_b32_e32 v84, v108
	v_mov_b32_e32 v85, v109
	v_pk_add_f32 v[76:77], v[76:77], v[64:65] neg_lo:[0,1] neg_hi:[0,1]
	v_mov_b32_e32 v57, v9
	v_pk_fma_f32 v[64:65], v[82:83], v[76:77], v[64:65]
	v_pk_add_f32 v[76:77], v[80:81], v[88:89] neg_lo:[0,1] neg_hi:[0,1]
	s_nop 0
	v_pk_fma_f32 v[76:77], v[0:1], v[76:77], v[88:89]
	v_pk_add_f32 v[0:1], v[62:63], v[86:87] neg_lo:[0,1] neg_hi:[0,1]
	s_nop 0
	v_pk_fma_f32 v[62:63], v[84:85], v[0:1], v[86:87]
	v_pk_add_f32 v[0:1], v[78:79], v[90:91] neg_lo:[0,1] neg_hi:[0,1]
	s_nop 0
	v_pk_fma_f32 v[78:79], v[2:3], v[0:1], v[90:91]
	v_cvt_pk_bf16_f32 v0, v64, v65
	v_cvt_pk_bf16_f32 v1, v62, v63
	v_cvt_pk_bf16_f32 v2, v76, v77
	v_cvt_pk_bf16_f32 v3, v78, v79
	global_store_dwordx4 v[74:75], v[0:3], off offset:3072
	v_mov_b32_e32 v62, 0
	v_mov_b32_e32 v74, 0
	v_lshl_add_u64 v[0:1], v[72:73], 0, v[56:57]
	v_mov_b32_e32 v0, v170
	v_mov_b32_e32 v1, v171
	v_mov_b32_e32 v2, v172
	v_mov_b32_e32 v3, v173
	v_mov_b32_e32 v75, 0
	v_mov_b32_e32 v64, 0
	v_mov_b32_e32 v65, 0
	v_mov_b32_e32 v78, 0
	v_mov_b32_e32 v79, 0
	v_mov_b32_e32 v76, 0
	v_mov_b32_e32 v77, 0
	s_and_saveexec_b64 s[0:1], s[44:45]
	s_cbranch_execz .LBB0_508
	v_lshl_add_u64 v[64:65], v[70:71], 0, v[56:57]
	v_mov_b32_e32 v78, v196
	v_mov_b32_e32 v79, v197
	v_mov_b32_e32 v80, v198
	v_mov_b32_e32 v81, v199
	v_lshlrev_b32_e32 v74, 16, v78
	v_and_b32_e32 v75, 0xffff0000, v78
	v_lshlrev_b32_e32 v64, 16, v79
	v_and_b32_e32 v65, 0xffff0000, v79
	v_lshlrev_b32_e32 v78, 16, v80
	v_and_b32_e32 v79, 0xffff0000, v80
	v_lshlrev_b32_e32 v76, 16, v81
	v_and_b32_e32 v77, 0xffff0000, v81
; __global__ void __launch_bounds__(NTHREADS, 2) fwd_megakernel(Args args) {
;     ...
;             for (int it = 0; it < 6; ++it) {
;                 const int c8 = (it * 64 + lane) * 8;
;                 float cur[8], prv[8], o[8];
;                 unpack8(*(const u32x4*)(pr + C_CR + c8), cur);
;                 if (t > 0) unpack8(*(const u32x4*)(pr - NP + C_CR + c8), prv);
;                 else {
; #pragma unroll
;                     for (int i = 0; i < 8; ++i) prv[i] = 0.f;
;                 }
;                 const float* mp = mu + (size_t)l * 3200 + c8;
;                 const f32x4 m0 = *(const f32x4*)mp, m1 = *(const f32x4*)(mp + 4);
; #pragma unroll
;                 for (int i = 0; i < 4; ++i) { o[i] = cur[i] + (prv[i] - cur[i]) * m0[i]; o[4 + i] = cur[4 + i] + (prv[4 + i] - cur[4 + i]) * m1[i]; }
;                 *(u32x4*)(CRKV + (size_t)r * 3072 + c8) = pack8(o);
;             }
;             if (lane < 16) {
;                 const int c8 = lane * 8;
;                 float cur[8], prv[8], o[8];
;                 unpack8(*(const u32x4*)(pr + C_WD + c8), cur);
;                 if (t > 0) unpack8(*(const u32x4*)(pr - NP + C_WD + c8), prv);
.LBB0_508:
	s_or_b64 exec, exec, s[0:1]
	v_lshlrev_b32_e32 v84, 16, v0
	v_and_b32_e32 v85, 0xffff0000, v0
	v_lshlrev_b32_e32 v86, 16, v1
	v_and_b32_e32 v87, 0xffff0000, v1
	v_lshlrev_b32_e32 v88, 16, v2
	v_and_b32_e32 v89, 0xffff0000, v2
	v_lshlrev_b32_e32 v90, 16, v3
	v_and_b32_e32 v91, 0xffff0000, v3
	v_mov_b32_e32 v0, v110
	v_mov_b32_e32 v1, v111
	v_mov_b32_e32 v2, v112
	v_mov_b32_e32 v3, v113
	v_mov_b32_e32 v80, v116
	v_mov_b32_e32 v81, v117
	v_mov_b32_e32 v82, v118
	v_mov_b32_e32 v83, v119
	v_pk_add_f32 v[78:79], v[78:79], v[88:89] neg_lo:[0,1] neg_hi:[0,1]
	v_pk_add_f32 v[74:75], v[74:75], v[84:85] neg_lo:[0,1] neg_hi:[0,1]
	v_lshl_add_u64 v[56:57], v[68:69], 0, v[56:57]
	v_mov_b32_e32 v59, v9
	v_mov_b32_e32 v63, 0
	v_pk_fma_f32 v[78:79], v[0:1], v[78:79], v[88:89]
	v_pk_add_f32 v[0:1], v[64:65], v[86:87] neg_lo:[0,1] neg_hi:[0,1]
	v_pk_fma_f32 v[74:75], v[80:81], v[74:75], v[84:85]
	v_pk_fma_f32 v[64:65], v[82:83], v[0:1], v[86:87]
	v_pk_add_f32 v[0:1], v[76:77], v[90:91] neg_lo:[0,1] neg_hi:[0,1]
	s_nop 0
	v_pk_fma_f32 v[76:77], v[2:3], v[0:1], v[90:91]
	v_cvt_pk_bf16_f32 v0, v74, v75
	v_cvt_pk_bf16_f32 v1, v64, v65
	v_cvt_pk_bf16_f32 v2, v78, v79
	v_cvt_pk_bf16_f32 v3, v76, v77
	global_store_dwordx4 v[56:57], v[0:3], off
	v_mov_b32_e32 v56, 0
	v_mov_b32_e32 v57, 0
	v_lshl_add_u64 v[0:1], v[72:73], 0, v[58:59]
	v_mov_b32_e32 v0, v174
	v_mov_b32_e32 v1, v175
	v_mov_b32_e32 v2, v176
	v_mov_b32_e32 v3, v177
	v_mov_b32_e32 v72, 0
	v_mov_b32_e32 v73, 0
	v_mov_b32_e32 v64, 0
	v_mov_b32_e32 v65, 0
	s_and_saveexec_b64 s[0:1], s[44:45]
	s_cbranch_execz .LBB0_510
	v_lshl_add_u64 v[56:57], v[70:71], 0, v[58:59]
	v_mov_b32_e32 v72, v200
	v_mov_b32_e32 v73, v201
	v_mov_b32_e32 v74, v202
	v_mov_b32_e32 v75, v203
	v_lshlrev_b32_e32 v62, 16, v72
	v_and_b32_e32 v63, 0xffff0000, v72
	v_lshlrev_b32_e32 v56, 16, v73
	v_and_b32_e32 v57, 0xffff0000, v73
	v_lshlrev_b32_e32 v72, 16, v74
	v_and_b32_e32 v73, 0xffff0000, v74
	v_lshlrev_b32_e32 v64, 16, v75
	v_and_b32_e32 v65, 0xffff0000, v75
.LBB0_510:
	s_or_b64 exec, exec, s[0:1]
	v_lshlrev_b32_e32 v70, 16, v0
	v_and_b32_e32 v71, 0xffff0000, v0
	v_lshlrev_b32_e32 v78, 16, v1
	v_and_b32_e32 v79, 0xffff0000, v1
	v_lshlrev_b32_e32 v80, 16, v2
	v_and_b32_e32 v81, 0xffff0000, v2
	v_lshlrev_b32_e32 v82, 16, v3
	v_and_b32_e32 v83, 0xffff0000, v3
	v_mov_b32_e32 v0, v120
	v_mov_b32_e32 v1, v121
	v_mov_b32_e32 v2, v122
	v_mov_b32_e32 v3, v123
	v_mov_b32_e32 v74, v136
	v_mov_b32_e32 v75, v137
	v_mov_b32_e32 v76, v138
	v_mov_b32_e32 v77, v139
	v_pk_add_f32 v[62:63], v[62:63], v[70:71] neg_lo:[0,1] neg_hi:[0,1]
	s_mov_b64 s[0:1], 0
	v_pk_fma_f32 v[62:63], v[74:75], v[62:63], v[70:71]
	v_pk_add_f32 v[70:71], v[72:73], v[80:81] neg_lo:[0,1] neg_hi:[0,1]
	s_nop 0
	v_pk_fma_f32 v[70:71], v[0:1], v[70:71], v[80:81]
	v_pk_add_f32 v[0:1], v[56:57], v[78:79] neg_lo:[0,1] neg_hi:[0,1]
	s_nop 0
	v_pk_fma_f32 v[56:57], v[76:77], v[0:1], v[78:79]
	v_pk_add_f32 v[0:1], v[64:65], v[82:83] neg_lo:[0,1] neg_hi:[0,1]
	s_nop 0
	v_pk_fma_f32 v[64:65], v[2:3], v[0:1], v[82:83]
	v_cvt_pk_bf16_f32 v0, v62, v63
	v_cvt_pk_bf16_f32 v1, v56, v57
	v_cvt_pk_bf16_f32 v2, v70, v71
	v_cvt_pk_bf16_f32 v3, v64, v65
	v_lshl_add_u64 v[56:57], v[68:69], 0, v[58:59]
	global_store_dwordx4 v[56:57], v[0:3], off
	s_and_saveexec_b64 s[24:25], s[40:41]
	s_xor_b64 s[46:47], exec, s[24:25]
	s_and_b64 s[0:1], s[42:43], exec
	s_or_saveexec_b64 s[46:47], s[46:47]
	v_mov_b32_e32 v3, 0
	v_mov_b32_e32 v2, 0
	v_mov_b32_e32 v1, 0
	v_mov_b32_e32 v0, 0
	s_xor_b64 exec, exec, s[46:47]
	s_cbranch_execz .LBB0_550
	v_mov_b32_e32 v55, v9
	v_lshl_add_u64 v[62:63], v[60:61], 0, v[54:55]
	v_add_co_u32_e32 v0, vcc, 0x9000, v62
	v_mov_b32_e32 v54, 0
	s_nop 0
	v_addc_co_u32_e32 v1, vcc, 0, v63, vcc
	global_load_dwordx4 v[0:3], v[0:1], off
	v_mov_b32_e32 v55, v54
	v_mov_b32_e32 v56, v54
	v_mov_b32_e32 v57, v54
	v_mov_b32_e32 v60, v54
	v_mov_b32_e32 v61, v54
	v_mov_b32_e32 v58, v54
	v_mov_b32_e32 v59, v54
	s_and_saveexec_b64 s[48:49], s[44:45]
	s_cbranch_execz .LBB0_515
	global_load_dwordx4 v[60:63], v[62:63], off offset:-512
	s_waitcnt vmcnt(0)
	v_lshlrev_b32_e32 v58, 16, v60
	v_and_b32_e32 v59, 0xffff0000, v60
	v_lshlrev_b32_e32 v56, 16, v61
	v_and_b32_e32 v57, 0xffff0000, v61
	v_lshlrev_b32_e32 v60, 16, v62
	v_and_b32_e32 v61, 0xffff0000, v62
	v_lshlrev_b32_e32 v54, 16, v63
	v_and_b32_e32 v55, 0xffff0000, v63

; #define LAS __attribute__((address_space(3)))
; __device__ __forceinline__ unsigned cvt_pk_bf16(float lo, float hi) { const bf16x2_t r = __builtin_convertvector((f32x2){lo, hi}, bf16x2_t); return __builtin_bit_cast(unsigned, r); }
; __device__ __forceinline__ float bflo(unsigned u) { return __uint_as_float(u << 16); }
; __device__ __forceinline__ float bfhi(unsigned u) { return __uint_as_float(u & 0xffff0000u); }
; #define LDS_BAR() do { asm volatile("s_waitcnt lgkmcnt(0)" ::: "memory"); __builtin_amdgcn_s_barrier(); asm volatile("" ::: "memory"); } while (0)
; __device__ __forceinline__ void rw_phaseB(LAS unsigned char* lds, const RwCtx& X, int bh) {
;     ...
;         for (int j = 0; j < 4; ++j) { const int c = c0 + j;
;             if (c < NCH) {
;                 LAS bf16_t* STb = (LAS bf16_t*)(lds + (c & 1) * 9216);
;                 bf16_t* sg = X.SRW + ((size_t)bh * NCH + c) * 4096;
; #pragma unroll
;                 for (int bi = 0; bi < 2; ++bi) { const int v0 = (vb0 + bi) * 16; u32x2 o; o.x = cvt_pk_bf16(acc[bi][0], acc[bi][1]); o.y = cvt_pk_bf16(acc[bi][2], acc[bi][3]);
;                     *(LAS u32x2*)(STb + (v0 + fr) * 72 + d0 + fq * 4) = o; *(u32x2*)(sg + (v0 + fr) * 64 + d0 + fq * 4) = o; }
;                 LDS_BAR();
; #pragma unroll
;                 for (int bi = 0; bi < 2; ++bi) { const int v0 = (vb0 + bi) * 16;
;                     f32x4 n = (f32x4){dc[j][0] * acc[bi][0] + bflo(rf[j][bi].x), dc[j][1] * acc[bi][1] + bfhi(rf[j][bi].x), dc[j][2] * acc[bi][2] + bflo(rf[j][bi].y), dc[j][3] * acc[bi][3] + bfhi(rf[j][bi].y)};
; #pragma unroll
;                     for (int k = 0; k < 2; ++k) { const bf16x8 fs = *(const LAS bf16x8*)(STb + (v0 + fr) * 72 + k * 32 + fq * 8); n = __builtin_amdgcn_mfma_f32_16x16x32_bf16(pa[j][k], fs, n, 0, 0, 0); }
;                     acc[bi] = n; }
.LBB0_1180:
	v_lshl_add_u64 v[162:163], s[92:93], 0, v[110:111]
	v_add_co_u32_e32 v140, vcc, s8, v162
	v_cvt_pk_bf16_f32 v138, v34, v35
	v_cvt_pk_bf16_f32 v139, v36, v37
	v_addc_co_u32_e32 v141, vcc, 0, v163, vcc
	v_lshl_add_u64 v[160:161], s[92:93], 0, v[112:113]
	v_mov_b64_e32 v[184:185], v[138:139]
	v_mov_b64_e32 v[188:189], v[140:141]
	v_add_co_u32_e32 v140, vcc, s8, v160
	ds_write_b64 v8, v[138:139]
	v_cvt_pk_bf16_f32 v138, v38, v39
	v_cvt_pk_bf16_f32 v139, v40, v41
	v_addc_co_u32_e32 v141, vcc, 0, v161, vcc
	ds_write_b64 v8, v[138:139] offset:2304
	v_mov_b64_e32 v[186:187], v[138:139]
	v_mov_b64_e32 v[190:191], v[140:141]
	v_lshlrev_b32_e32 v138, 16, v158
	v_and_b32_e32 v139, 0xffff0000, v158
	s_waitcnt lgkmcnt(0)
	s_barrier
	ds_read_b128 v[168:171], v146
	ds_read_b128 v[172:175], v146 offset:64
	ds_read_b128 v[176:179], v146 offset:2304
	ds_read_b128 v[180:183], v146 offset:2368
	v_pk_fma_f32 v[34:35], v[34:35], v[98:99], v[138:139]
	v_lshlrev_b32_e32 v138, 16, v159
	v_and_b32_e32 v139, 0xffff0000, v159
	v_pk_fma_f32 v[36:37], v[36:37], v[100:101], v[138:139]
	s_nop 0
	s_add_i32 s0, s6, -2
	s_waitcnt lgkmcnt(3)
	v_mfma_f32_16x16x32_bf16 v[34:37], v[94:97], v[168:171], v[34:37]
	s_nop 0
	s_cmpk_gt_u32 s0, 0x80
	s_waitcnt lgkmcnt(2)
	v_mfma_f32_16x16x32_bf16 v[34:37], v[90:93], v[172:175], v[34:37]
	v_lshlrev_b32_e32 v138, 16, v156
	v_and_b32_e32 v139, 0xffff0000, v156
	v_pk_fma_f32 v[38:39], v[38:39], v[98:99], v[138:139]
	v_lshlrev_b32_e32 v98, 16, v157
	v_and_b32_e32 v99, 0xffff0000, v157
	v_pk_fma_f32 v[40:41], v[40:41], v[100:101], v[98:99]
	s_nop 0
	s_waitcnt lgkmcnt(1)
	v_mfma_f32_16x16x32_bf16 v[38:41], v[94:97], v[176:179], v[38:41]
	s_nop 0
	s_waitcnt lgkmcnt(0)
	v_mfma_f32_16x16x32_bf16 v[38:41], v[90:93], v[180:183], v[38:41]
	global_store_dwordx2 v[188:189], v[184:185], off
	global_store_dwordx2 v[190:191], v[186:187], off
	s_cbranch_scc0 .LBB0_1183
	s_add_i32 s0, s6, -1
	s_cmpk_gt_u32 s0, 0x80
	s_cbranch_scc0 .LBB0_1184

; #define LAS __attribute__((address_space(3)))
; __device__ __forceinline__ unsigned cvt_pk_bf16(float lo, float hi) { const bf16x2_t r = __builtin_convertvector((f32x2){lo, hi}, bf16x2_t); return __builtin_bit_cast(unsigned, r); }
; __device__ __forceinline__ float bflo(unsigned u) { return __uint_as_float(u << 16); }
; __device__ __forceinline__ float bfhi(unsigned u) { return __uint_as_float(u & 0xffff0000u); }
; #define LDS_BAR() do { asm volatile("s_waitcnt lgkmcnt(0)" ::: "memory"); __builtin_amdgcn_s_barrier(); asm volatile("" ::: "memory"); } while (0)
; __device__ __forceinline__ void rw_phaseB(LAS unsigned char* lds, const RwCtx& X, int bh) {
;     ...
;         for (int j = 0; j < 4; ++j) { const int c = c0 + j;
;             if (c < NCH) {
;                 LAS bf16_t* STb = (LAS bf16_t*)(lds + (c & 1) * 9216);
;                 bf16_t* sg = X.SRW + ((size_t)bh * NCH + c) * 4096;
; #pragma unroll
;                 for (int bi = 0; bi < 2; ++bi) { const int v0 = (vb0 + bi) * 16; u32x2 o; o.x = cvt_pk_bf16(acc[bi][0], acc[bi][1]); o.y = cvt_pk_bf16(acc[bi][2], acc[bi][3]);
;                     *(LAS u32x2*)(STb + (v0 + fr) * 72 + d0 + fq * 4) = o; *(u32x2*)(sg + (v0 + fr) * 64 + d0 + fq * 4) = o; }
;                 LDS_BAR();
; #pragma unroll
;                 for (int bi = 0; bi < 2; ++bi) { const int v0 = (vb0 + bi) * 16;
;                     f32x4 n = (f32x4){dc[j][0] * acc[bi][0] + bflo(rf[j][bi].x), dc[j][1] * acc[bi][1] + bfhi(rf[j][bi].x), dc[j][2] * acc[bi][2] + bflo(rf[j][bi].y), dc[j][3] * acc[bi][3] + bfhi(rf[j][bi].y)};
; #pragma unroll
;                     for (int k = 0; k < 2; ++k) { const bf16x8 fs = *(const LAS bf16x8*)(STb + (v0 + fr) * 72 + k * 32 + fq * 8); n = __builtin_amdgcn_mfma_f32_16x16x32_bf16(pa[j][k], fs, n, 0, 0, 0); }
;                     acc[bi] = n; }
.LBB0_1183:
	v_add_co_u32_e32 v92, vcc, 0x7814e000, v162
	v_cvt_pk_bf16_f32 v90, v34, v35
	v_cvt_pk_bf16_f32 v91, v36, v37
	v_addc_co_u32_e32 v93, vcc, 0, v163, vcc
	s_mov_b32 s0, 0x7814e000
	v_mov_b64_e32 v[184:185], v[90:91]
	v_mov_b64_e32 v[188:189], v[92:93]
	v_add_co_u32_e32 v92, vcc, s0, v160
	ds_write_b64 v8, v[90:91] offset:9216
	v_cvt_pk_bf16_f32 v90, v38, v39
	v_cvt_pk_bf16_f32 v91, v40, v41
	v_addc_co_u32_e32 v93, vcc, 0, v161, vcc
	ds_write_b64 v8, v[90:91] offset:11520
	v_mov_b64_e32 v[186:187], v[90:91]
	v_mov_b64_e32 v[190:191], v[92:93]
	v_lshlrev_b32_e32 v90, 16, v154
	v_and_b32_e32 v91, 0xffff0000, v154
	s_waitcnt lgkmcnt(0)
	s_barrier
	ds_read_b128 v[168:171], v146 offset:9216
	ds_read_b128 v[172:175], v146 offset:9280
	ds_read_b128 v[176:179], v146 offset:11520
	ds_read_b128 v[180:183], v146 offset:11584
	v_pk_fma_f32 v[34:35], v[86:87], v[34:35], v[90:91]
	v_lshlrev_b32_e32 v90, 16, v155
	v_and_b32_e32 v91, 0xffff0000, v155
	v_pk_fma_f32 v[36:37], v[88:89], v[36:37], v[90:91]
	s_nop 0
	s_waitcnt lgkmcnt(3)
	v_mfma_f32_16x16x32_bf16 v[34:37], v[74:77], v[168:171], v[34:37]
	s_nop 0
	s_waitcnt lgkmcnt(2)
	v_mfma_f32_16x16x32_bf16 v[34:37], v[70:73], v[172:175], v[34:37]
	v_lshlrev_b32_e32 v90, 16, v148
	v_and_b32_e32 v91, 0xffff0000, v148
	v_pk_fma_f32 v[38:39], v[86:87], v[38:39], v[90:91]
	v_lshlrev_b32_e32 v86, 16, v149
	v_and_b32_e32 v87, 0xffff0000, v149
	v_pk_fma_f32 v[40:41], v[88:89], v[40:41], v[86:87]
	s_nop 0
	s_waitcnt lgkmcnt(1)
	v_mfma_f32_16x16x32_bf16 v[38:41], v[74:77], v[176:179], v[38:41]
	s_nop 0
	s_waitcnt lgkmcnt(0)
	v_mfma_f32_16x16x32_bf16 v[38:41], v[70:73], v[180:183], v[38:41]
	global_store_dwordx2 v[188:189], v[184:185], off
	global_store_dwordx2 v[190:191], v[186:187], off
	s_add_i32 s0, s6, -1
	s_cmpk_gt_u32 s0, 0x80
	s_cbranch_scc1 .LBB0_1182
.LBB0_1184:
	v_add_co_u32_e32 v72, vcc, 0x78150000, v162
	v_cvt_pk_bf16_f32 v70, v34, v35
	v_cvt_pk_bf16_f32 v71, v36, v37
	v_addc_co_u32_e32 v73, vcc, 0, v163, vcc
	s_mov_b32 s0, 0x78150000
	v_mov_b64_e32 v[184:185], v[70:71]
	v_mov_b64_e32 v[188:189], v[72:73]
	v_add_co_u32_e32 v72, vcc, s0, v160
	ds_write_b64 v8, v[70:71]
	v_cvt_pk_bf16_f32 v70, v38, v39
	v_cvt_pk_bf16_f32 v71, v40, v41
	v_addc_co_u32_e32 v73, vcc, 0, v161, vcc
	ds_write_b64 v8, v[70:71] offset:2304
	v_mov_b64_e32 v[186:187], v[70:71]
	v_mov_b64_e32 v[190:191], v[72:73]
	v_lshlrev_b32_e32 v70, 16, v132
	v_and_b32_e32 v71, 0xffff0000, v132
	s_waitcnt lgkmcnt(0)
	s_barrier
	ds_read_b128 v[168:171], v146
	ds_read_b128 v[172:175], v146 offset:64
	ds_read_b128 v[176:179], v146 offset:2304
	ds_read_b128 v[180:183], v146 offset:2368
	v_pk_fma_f32 v[34:35], v[46:47], v[34:35], v[70:71]
	v_lshlrev_b32_e32 v70, 16, v133
	v_and_b32_e32 v71, 0xffff0000, v133
	v_pk_fma_f32 v[36:37], v[48:49], v[36:37], v[70:71]
	s_nop 0
	s_waitcnt lgkmcnt(3)
	v_mfma_f32_16x16x32_bf16 v[34:37], v[30:33], v[168:171], v[34:37]
	s_nop 0
	s_waitcnt lgkmcnt(2)
	v_mfma_f32_16x16x32_bf16 v[34:37], v[14:17], v[172:175], v[34:37]
	v_lshlrev_b32_e32 v70, 16, v126
	v_and_b32_e32 v71, 0xffff0000, v126
	v_pk_fma_f32 v[38:39], v[46:47], v[38:39], v[70:71]
	v_lshlrev_b32_e32 v46, 16, v127
	v_and_b32_e32 v47, 0xffff0000, v127
	v_pk_fma_f32 v[40:41], v[48:49], v[40:41], v[46:47]
	s_nop 0
	s_waitcnt lgkmcnt(1)
	v_mfma_f32_16x16x32_bf16 v[30:33], v[30:33], v[176:179], v[38:41]
	s_nop 2
	s_nop 0
	s_waitcnt lgkmcnt(0)
	v_mfma_f32_16x16x32_bf16 v[38:41], v[14:17], v[180:183], v[30:33]
	global_store_dwordx2 v[188:189], v[184:185], off
	global_store_dwordx2 v[190:191], v[186:187], off
	s_cmpk_gt_u32 s6, 0x80
	s_cbranch_scc1 .LBB0_1165
.LBB0_1185:
	v_add_co_u32_e32 v16, vcc, 0x78152000, v162
	v_cvt_pk_bf16_f32 v14, v34, v35
	v_cvt_pk_bf16_f32 v15, v36, v37
	v_addc_co_u32_e32 v17, vcc, 0, v163, vcc
	s_mov_b32 s0, 0x78152000
	v_mov_b64_e32 v[184:185], v[14:15]
	v_mov_b64_e32 v[188:189], v[16:17]
	v_add_co_u32_e32 v16, vcc, s0, v160
	ds_write_b64 v8, v[14:15] offset:9216
	v_cvt_pk_bf16_f32 v14, v38, v39
	v_cvt_pk_bf16_f32 v15, v40, v41
	v_addc_co_u32_e32 v17, vcc, 0, v161, vcc
	ds_write_b64 v8, v[14:15] offset:11520
	v_mov_b64_e32 v[186:187], v[14:15]
	v_mov_b64_e32 v[190:191], v[16:17]
	s_waitcnt lgkmcnt(0)
	s_barrier
	ds_read_b128 v[168:171], v146 offset:9216
	ds_read_b128 v[172:175], v146 offset:9280
	ds_read_b128 v[176:179], v146 offset:11520
	ds_read_b128 v[180:183], v146 offset:11584
	s_nop 0
	v_lshlrev_b32_e32 v14, 16, v116
	v_and_b32_e32 v15, 0xffff0000, v116
	v_lshlrev_b32_e32 v16, 16, v117
	v_and_b32_e32 v17, 0xffff0000, v117
	v_pk_fma_f32 v[14:15], v[120:121], v[34:35], v[14:15]
	v_pk_fma_f32 v[16:17], v[122:123], v[36:37], v[16:17]
	s_waitcnt lgkmcnt(3)
	s_nop 0
	v_mfma_f32_16x16x32_bf16 v[14:17], v[10:13], v[168:171], v[14:17]
	s_nop 0
	s_waitcnt lgkmcnt(2)
	v_mfma_f32_16x16x32_bf16 v[34:37], v[4:7], v[172:175], v[14:17]
	s_nop 0
	s_nop 3
	v_lshlrev_b32_e32 v14, 16, v114
	v_and_b32_e32 v15, 0xffff0000, v114
	v_lshlrev_b32_e32 v16, 16, v115
	v_and_b32_e32 v17, 0xffff0000, v115
	v_pk_fma_f32 v[14:15], v[120:121], v[38:39], v[14:15]
	v_pk_fma_f32 v[16:17], v[122:123], v[40:41], v[16:17]
	s_waitcnt lgkmcnt(1)
	s_nop 0
	v_mfma_f32_16x16x32_bf16 v[10:13], v[10:13], v[176:179], v[14:17]
	s_nop 2
	s_nop 0
	s_waitcnt lgkmcnt(0)
	v_mfma_f32_16x16x32_bf16 v[38:41], v[4:7], v[180:183], v[10:13]
	global_store_dwordx2 v[188:189], v[184:185], off
	global_store_dwordx2 v[190:191], v[186:187], off
	s_branch .LBB0_1165

; #define LAS __attribute__((address_space(3)))
; __device__ __forceinline__ float bf1(bf16_t b) { return __uint_as_float(((unsigned)b) << 16); }
; __device__ __forceinline__ void rw_prep(LAS float* SCR, const RwCtx& X, int b, int h, int t0, int tid, RwTok& K) {
;     const int t = tid >> 3, dq = tid & 7, lane = tid & 63, wave = tid >> 6;
;     const int tt = t0 + t; const bool ok = tt < T; const size_t row = (size_t)b * T + (ok ? tt : 0);
;     const bf16_t* pr = X.CRKV + row * 3072 + h * 64 + dq * 8;
;     float kr[8], aa[8];
;     unpack8(*(const u32x4*)pr, K.r); unpack8(*(const u32x4*)(pr + 1024), kr); unpack8(*(const u32x4*)(pr + 2048), K.v);
;     unpack8(*(const u32x4*)(X.CA + row * 1024 + h * 64 + dq * 8), aa); unpack8(*(const u32x4*)(X.CW + row * 1024 + h * 64 + dq * 8), K.lw);
;     const f32x4 p0 = *(const f32x4*)(X.kkp + h * 64 + dq * 8), p1 = *(const f32x4*)(X.kkp + h * 64 + dq * 8 + 4);
;     const f32x4 q0 = *(const f32x4*)(X.kap + h * 64 + dq * 8), q1 = *(const f32x4*)(X.kap + h * 64 + dq * 8 + 4);
; __device__ __forceinline__ void rw_phaseC(LAS unsigned char* lds, const RwCtx& X, int item) {
;     ...
;     { const bf16_t* u0g = (const bf16_t*)(gi + RWI_U);
; #pragma unroll
;       for (int bi = 0; bi < 2; ++bi)
; #pragma unroll
;         for (int j = 0; j < 4; ++j) u0v[bi][j] = bf1(u0g[(t0b + fq * 4 + j) * 64 + ((wave & 1) * 2 + bi) * 16 + fr]); }
;     {
;         *(LAS u32x4*)(ST + t * 72 + dq * 8) = *(const u32x4*)(X.SRW + (size_t)item * 4096 + t * 64 + dq * 8);
;         *(LAS u32x4*)(Wt + t * 72 + dq * 8) = *(const u32x4*)(gi + RWI_W + ((size_t)t * 64 + dq * 8) * 2);
;     }
.LBB0_1245:
	v_mov_b32_e32 v47, v226
	s_mul_hi_i32 s0, s62, 0xfe03f81
	v_ashrrev_i32_e32 v36, 6, v47
	v_bfe_u32 v67, v47, 4, 2
	v_ashrrev_i32_e32 v34, 3, v47
	s_lshr_b32 s1, s0, 31
	s_ashr_i32 s28, s0, 3
	v_and_b32_e32 v55, -16, v34
	v_lshlrev_b32_e32 v61, 2, v67
	v_lshlrev_b32_e32 v1, 5, v36
	v_and_b32_e32 v54, 15, v47
	s_add_i32 s28, s28, s1
	v_or_b32_e32 v0, v61, v55
	v_and_b32_e32 v66, 32, v1
	s_ashr_i32 s63, s28, 4
	v_lshlrev_b32_e32 v2, 6, v0
	v_or_b32_e32 v56, v66, v54
	v_or_b32_e32 v0, v2, v56
	s_add_u32 s0, s92, s6
	v_ashrrev_i32_e32 v1, 31, v0
	s_addc_u32 s1, s93, s7
	v_lshl_add_u64 v[0:1], v[0:1], 1, s[0:1]
	v_add_co_u32_e32 v0, vcc, s60, v0
	v_or_b32_e32 v3, 64, v2
	s_nop 0
	v_addc_co_u32_e32 v1, vcc, 0, v1, vcc
	global_load_ushort v65, v[0:1], off offset:256
	v_or_b32_e32 v0, v3, v56
	v_ashrrev_i32_e32 v1, 31, v0
	v_lshl_add_u64 v[0:1], v[0:1], 1, s[0:1]
	v_add_co_u32_e32 v0, vcc, s60, v0
	v_or_b32_e32 v4, 0x80, v2
	s_nop 0
	v_addc_co_u32_e32 v1, vcc, 0, v1, vcc
	global_load_ushort v57, v[0:1], off offset:256
	v_or_b32_e32 v0, v4, v56
	v_ashrrev_i32_e32 v1, 31, v0
	v_lshl_add_u64 v[0:1], v[0:1], 1, s[0:1]
	v_add_co_u32_e32 v0, vcc, s60, v0
	v_or_b32_e32 v5, 0xc0, v2
	s_nop 0
	v_addc_co_u32_e32 v1, vcc, 0, v1, vcc
	global_load_ushort v60, v[0:1], off offset:256
	v_or_b32_e32 v0, v5, v56
	v_ashrrev_i32_e32 v1, 31, v0
	v_lshl_add_u64 v[0:1], v[0:1], 1, s[0:1]
	v_add_co_u32_e32 v0, vcc, s60, v0
	v_or_b32_e32 v6, 16, v56
	s_nop 0
	v_addc_co_u32_e32 v1, vcc, 0, v1, vcc
	global_load_ushort v63, v[0:1], off offset:256
	v_or_b32_e32 v0, v2, v6
	v_ashrrev_i32_e32 v1, 31, v0
	v_lshl_add_u64 v[0:1], v[0:1], 1, s[0:1]
	v_add_co_u32_e32 v0, vcc, s60, v0
	v_and_b32_e32 v68, 7, v47
	s_nop 0
	v_addc_co_u32_e32 v1, vcc, 0, v1, vcc
	global_load_ushort v64, v[0:1], off offset:256
	v_or_b32_e32 v0, v3, v6
	v_ashrrev_i32_e32 v1, 31, v0
	v_lshl_add_u64 v[0:1], v[0:1], 1, s[0:1]
	v_add_co_u32_e32 v0, vcc, s60, v0
	s_add_u32 s24, s92, s26
	s_nop 0
	v_addc_co_u32_e32 v1, vcc, 0, v1, vcc
	global_load_ushort v58, v[0:1], off offset:256
	v_or_b32_e32 v0, v4, v6
	v_ashrrev_i32_e32 v1, 31, v0
	v_lshl_add_u64 v[0:1], v[0:1], 1, s[0:1]
	v_add_co_u32_e32 v0, vcc, s60, v0
	v_lshlrev_b32_e32 v4, 4, v68
	s_nop 0
	v_addc_co_u32_e32 v1, vcc, 0, v1, vcc
	global_load_ushort v59, v[0:1], off offset:256
	v_or_b32_e32 v0, v5, v6
	v_ashrrev_i32_e32 v1, 31, v0
	v_lshl_add_u64 v[0:1], v[0:1], 1, s[0:1]
	v_add_co_u32_e32 v0, vcc, s60, v0
	s_addc_u32 s25, s93, s27
	s_nop 0
	v_addc_co_u32_e32 v1, vcc, 0, v1, vcc
	global_load_ushort v62, v[0:1], off offset:256
	v_lshlrev_b32_e32 v0, 6, v34
	v_ashrrev_i32_e32 v1, 31, v0
	v_lshlrev_b64 v[0:1], 1, v[0:1]
	v_or_b32_e32 v0, v0, v4
	v_lshl_add_u64 v[0:1], s[24:25], 0, v[0:1]
	global_load_dwordx4 v[156:159], v[0:1], off
	v_mul_lo_u32 v5, v34, s91
	v_add3_u32 v5, 0, v5, v4
	v_ashrrev_i32_e32 v35, 31, v34
	s_mul_i32 s64, s28, 0x2040
	v_readlane_b32 s8, v252, 7
	v_readlane_b32 s9, v252, 8
	v_and_b32_e32 v69, 63, v47
	v_cmp_gt_u32_e64 s[48:49], 8, v69
	v_cmp_gt_u32_e64 s[46:47], 16, v69
	v_mov_b32_e32 v224, v5
	v_lshlrev_b64 v[0:1], 7, v[34:35]
	v_or_b32_e32 v0, v0, v4
	v_lshl_add_u64 v[0:1], s[0:1], 0, v[0:1]
	s_mov_b32 s0, 0x6ff4e000
	v_add_co_u32_e32 v0, vcc, s0, v0
	v_lshlrev_b32_e32 v4, 3, v47
	s_nop 0
	v_addc_co_u32_e32 v1, vcc, 0, v1, vcc
	global_load_dwordx4 v[160:163], v[0:1], off offset:256
	v_and_b32_e32 v35, 56, v4
	v_lshlrev_b32_e32 v8, 1, v35
	v_lshlrev_b32_e32 v49, 2, v35
	v_subrev_u32_e32 v0, s64, v34
	v_add_u32_e32 v0, s61, v0
	v_cmp_gt_i32_e64 s[42:43], s82, v0
	v_mov_b64_e32 v[2:3], s[14:15]
	s_nop 0
	v_cndmask_b32_e64 v0, 0, v0, s[42:43]
	v_ashrrev_i32_e32 v1, 31, v0
	v_mad_i64_i32 v[0:1], s[0:1], s63, v243, v[0:1]
	v_mad_u64_u32 v[2:3], s[0:1], v0, s37, v[2:3]
	s_lshl_b32 s0, s28, 6
	s_and_b32 s0, s0, 0x3c0
	v_mad_i32_i24 v3, v1, s37, v3
	s_lshl_b32 s68, s0, 1
	v_lshl_add_u64 v[2:3], v[2:3], 0, s[68:69]
	v_lshl_add_u64 v[2:3], v[2:3], 0, v[8:9]
	s_movk_i32 s1, 0x1000
	global_load_dwordx4 v[4:7], v[2:3], off
	global_load_dwordx4 v[22:25], v[2:3], off offset:2048
	v_add_co_u32_e32 v2, vcc, s1, v2
	v_lshlrev_b64 v[0:1], 11, v[0:1]
	s_nop 0
	v_addc_co_u32_e32 v3, vcc, 0, v3, vcc
	global_load_dwordx4 v[10:13], v[2:3], off
	v_lshl_add_u64 v[2:3], s[72:73], 0, v[0:1]
	v_lshl_add_u64 v[0:1], s[8:9], 0, v[0:1]
	v_lshl_add_u64 v[2:3], v[2:3], 0, s[68:69]
	v_lshl_add_u64 v[0:1], v[0:1], 0, s[68:69]
	v_lshl_add_u64 v[2:3], v[2:3], 0, v[8:9]
	v_lshl_add_u64 v[0:1], v[0:1], 0, v[8:9]
	global_load_dwordx4 v[18:21], v[2:3], off
	s_lshl_b32 s8, s0, 2
	global_load_dwordx4 v[0:3], v[0:1], off
	s_add_u32 s0, s70, s8
	s_addc_u32 s1, s71, 0
	global_load_dwordx4 v[26:29], v49, s[0:1]
	global_load_dwordx4 v[30:33], v49, s[0:1] offset:16
	s_add_u32 s0, s86, s8
	s_addc_u32 s1, s87, 0
	v_cmp_lt_i32_e32 vcc, v229, v228
	s_waitcnt vmcnt(5)
	ds_write_b128 v224, v[156:159] offset:46080
	ds_write_b128 v224, v[160:163] offset:55296
	v_and_b32_e32 v37, 0xffff0000, v22
	v_cndmask_b32_e32 v8, v227, v229, vcc
	v_cmp_lt_i32_e32 vcc, v230, v228
	v_and_b32_e32 v43, 0xffff0000, v23
	v_lshlrev_b32_e32 v42, 16, v23
	v_cndmask_b32_e32 v23, v227, v230, vcc
	v_cmp_lt_i32_e32 vcc, v231, v228
	v_lshlrev_b32_e32 v52, 16, v22
	v_and_b32_e32 v39, 0xffff0000, v24
	v_lshlrev_b32_e32 v38, 16, v24
	v_lshlrev_b32_e32 v8, 2, v8
	v_lshlrev_b32_e32 v23, 2, v23
	s_waitcnt vmcnt(3)
; __device__ __forceinline__ void rw_prep(LAS float* SCR, const RwCtx& X, int b, int h, int t0, int tid, RwTok& K) {
;     ...
;     float kk[8]; float ss = 0.f;
; #pragma unroll
;     for (int i = 0; i < 8; ++i) { kk[i] = kr[i] * (i < 4 ? p0[i & 3] : p1[i & 3]); ss += kk[i] * kk[i]; }
;     ss += __shfl_xor(ss, 1); ss += __shfl_xor(ss, 2); ss += __shfl_xor(ss, 4);
;     const float inv = 1.0f / fmaxf(sqrtf(ss), 1e-12f);
; #pragma unroll
;     for (int i = 0; i < 8; ++i) { const float kn = kk[i] * inv, ka = (i < 4 ? q0[i & 3] : q1[i & 3]);
;         K.av[i] = -kn; K.bv[i] = kn * aa[i]; K.kp[i] = kr[i] * (1.0f + (aa[i] - 1.0f) * ka);
;         if (!ok) { K.av[i] = 0.f; K.bv[i] = 0.f; K.kp[i] = 0.f; K.r[i] = 0.f; K.v[i] = 0.f; K.lw[i] = 0.f; } }
; #pragma unroll
;     for (int i = 0; i < 8; ++i) { float x = K.lw[i];
; #pragma unroll
;         for (int o = 8; o < 64; o <<= 1) { const float y = __shfl_up(x, o); if (lane >= o) x += y; }
;         K.cw[i] = x; }
;     if ((lane >> 3) == 7) {
; #pragma unroll
;         for (int i = 0; i < 8; ++i) SCR[wave * 64 + dq * 8 + i] = K.cw[i];
;     }
	v_lshlrev_b32_e32 v48, 16, v18
	v_add_f32_e32 v53, -1.0, v48
	s_waitcnt vmcnt(2)
	v_lshlrev_b32_e32 v72, 16, v0
	v_and_b32_e32 v73, 0xffff0000, v0
	v_lshlrev_b32_e32 v74, 16, v1
	v_and_b32_e32 v75, 0xffff0000, v1
	v_lshlrev_b32_e32 v76, 16, v2
	v_and_b32_e32 v77, 0xffff0000, v2
	v_lshlrev_b32_e32 v78, 16, v3
	v_and_b32_e32 v79, 0xffff0000, v3
	global_load_dwordx4 v[0:3], v49, s[0:1] offset:16
	global_load_dwordx4 v[14:17], v49, s[0:1]
	s_waitcnt vmcnt(3)
	v_mul_f32_e32 v46, v27, v37
	v_cndmask_b32_e32 v27, v227, v231, vcc
	v_lshlrev_b32_e32 v80, 2, v27
	v_pk_mul_f32 v[44:45], v[28:29], v[42:43]
	s_waitcnt vmcnt(2)
	v_pk_mul_f32 v[40:41], v[30:31], v[38:39]
	v_pk_mul_f32 v[28:29], v[44:45], v[44:45]
	v_pk_mul_f32 v[70:71], v[40:41], v[40:41]
	v_and_b32_e32 v31, 0xffff0000, v25
	v_lshlrev_b32_e32 v30, 16, v25
	v_pk_mul_f32 v[32:33], v[32:33], v[30:31]
	v_cndmask_b32_e64 v22, 0, v72, s[42:43]
	v_pk_mul_f32 v[24:25], v[32:33], v[32:33]
	v_cndmask_b32_e64 v72, 0, v78, s[42:43]
	s_waitcnt vmcnt(0)
	v_mov_b32_e32 v27, v14
	v_pk_mul_f32 v[50:51], v[26:27], v[52:53]
	v_add_u32_e32 v26, -8, v227
	v_mul_f32_e32 v14, v50, v50
	v_fmac_f32_e32 v14, v46, v46
	v_add_f32_e32 v14, v28, v14
	v_add_f32_e32 v14, v29, v14
	v_add_f32_e32 v14, v70, v14
	v_add_f32_e32 v14, v71, v14
	v_add_f32_e32 v14, v24, v14
	v_add_f32_e32 v14, v25, v14
	ds_bpermute_b32 v8, v8, v14
	v_cmp_lt_i32_e32 vcc, v26, v240
	v_add_u32_e32 v27, -16, v227
	v_cndmask_b32_e64 v24, 0, v74, s[42:43]
	v_cndmask_b32_e32 v26, v26, v227, vcc
	v_cmp_lt_i32_e32 vcc, v27, v240
	s_waitcnt lgkmcnt(0)
	v_add_f32_e32 v8, v14, v8
	ds_bpermute_b32 v14, v23, v8
	v_cndmask_b32_e32 v27, v27, v227, vcc
	v_lshlrev_b32_e32 v74, 2, v27
	v_subrev_u32_e32 v27, 32, v227
	v_cmp_lt_i32_e32 vcc, v27, v240
	v_cndmask_b32_e64 v23, 0, v73, s[42:43]
	v_cndmask_b32_e64 v25, 0, v75, s[42:43]
	v_lshlrev_b32_e32 v53, 2, v26
	v_cndmask_b32_e32 v27, v27, v227, vcc
	ds_bpermute_b32 v26, v53, v22
	v_lshlrev_b32_e32 v75, 2, v27
	ds_bpermute_b32 v27, v53, v23
	ds_bpermute_b32 v28, v53, v24
	ds_bpermute_b32 v29, v53, v25
	v_cndmask_b32_e64 v70, 0, v76, s[42:43]
	v_cndmask_b32_e64 v71, 0, v77, s[42:43]
	s_waitcnt lgkmcnt(2)
	v_pk_add_f32 v[26:27], v[22:23], v[26:27]
	v_cndmask_b32_e64 v73, 0, v79, s[42:43]
	s_waitcnt lgkmcnt(0)
	v_pk_add_f32 v[28:29], v[24:25], v[28:29]
	v_cndmask_b32_e64 v23, v27, v23, s[48:49]
	v_cndmask_b32_e64 v25, v29, v25, s[48:49]
	v_cndmask_b32_e64 v24, v28, v24, s[48:49]
	v_cndmask_b32_e64 v22, v26, v22, s[48:49]
	ds_bpermute_b32 v26, v74, v22
	ds_bpermute_b32 v27, v74, v23
	ds_bpermute_b32 v28, v74, v24
	ds_bpermute_b32 v29, v74, v25
	v_cmp_gt_u32_e32 vcc, 32, v69
	v_add_f32_e32 v8, v8, v14
	s_waitcnt lgkmcnt(2)
	v_pk_add_f32 v[26:27], v[22:23], v[26:27]
	ds_bpermute_b32 v14, v80, v8
	s_waitcnt lgkmcnt(1)
	v_pk_add_f32 v[28:29], v[24:25], v[28:29]
	v_cndmask_b32_e64 v23, v27, v23, s[46:47]
	v_cndmask_b32_e64 v25, v29, v25, s[46:47]
	v_cndmask_b32_e64 v24, v28, v24, s[46:47]
	v_cndmask_b32_e64 v22, v26, v22, s[46:47]
	ds_bpermute_b32 v26, v75, v22
	ds_bpermute_b32 v27, v75, v23
	ds_bpermute_b32 v28, v75, v24
	ds_bpermute_b32 v29, v75, v25
	s_waitcnt lgkmcnt(2)
	v_pk_add_f32 v[26:27], v[22:23], v[26:27]
	s_nop 0
	v_cndmask_b32_e32 v27, v27, v23, vcc
	s_waitcnt lgkmcnt(0)
	v_pk_add_f32 v[28:29], v[24:25], v[28:29]
	v_cndmask_b32_e32 v26, v26, v22, vcc
	v_cndmask_b32_e32 v29, v29, v25, vcc
	v_cndmask_b32_e32 v28, v28, v24, vcc
	ds_bpermute_b32 v22, v53, v70
	ds_bpermute_b32 v23, v53, v71
	ds_bpermute_b32 v24, v53, v72
	ds_bpermute_b32 v25, v53, v73
	v_and_b32_e32 v53, 56, v47
	s_waitcnt lgkmcnt(2)
	v_pk_add_f32 v[22:23], v[70:71], v[22:23]
	s_nop 0
	v_cndmask_b32_e64 v23, v23, v71, s[48:49]
	s_waitcnt lgkmcnt(0)
	v_pk_add_f32 v[24:25], v[72:73], v[24:25]
	v_cndmask_b32_e64 v22, v22, v70, s[48:49]
	v_cndmask_b32_e64 v25, v25, v73, s[48:49]
	v_cndmask_b32_e64 v24, v24, v72, s[48:49]
	ds_bpermute_b32 v70, v74, v22
	ds_bpermute_b32 v71, v74, v23
	ds_bpermute_b32 v72, v74, v24
	ds_bpermute_b32 v73, v74, v25
	s_waitcnt lgkmcnt(2)
	v_pk_add_f32 v[70:71], v[22:23], v[70:71]
	s_nop 0
	v_cndmask_b32_e64 v23, v71, v23, s[46:47]
	s_waitcnt lgkmcnt(0)
	v_pk_add_f32 v[72:73], v[24:25], v[72:73]
	v_cndmask_b32_e64 v22, v70, v22, s[46:47]
	v_cndmask_b32_e64 v25, v73, v25, s[46:47]
	v_cndmask_b32_e64 v24, v72, v24, s[46:47]
	ds_bpermute_b32 v70, v75, v22
	ds_bpermute_b32 v71, v75, v23
	ds_bpermute_b32 v72, v75, v24
	ds_bpermute_b32 v73, v75, v25
	s_waitcnt lgkmcnt(2)
	v_pk_add_f32 v[70:71], v[22:23], v[70:71]
	s_nop 0
	v_cndmask_b32_e32 v23, v71, v23, vcc
	s_waitcnt lgkmcnt(0)
	v_pk_add_f32 v[72:73], v[24:25], v[72:73]
	v_cndmask_b32_e32 v22, v70, v22, vcc
	v_cndmask_b32_e32 v25, v73, v25, vcc
	v_cndmask_b32_e32 v24, v72, v24, vcc
	v_cmp_eq_u32_e32 vcc, 56, v53
	s_and_saveexec_b64 s[0:1], vcc
	s_cbranch_execz .LBB0_1247
	v_and_b32_e32 v47, 0x3fffffc0, v47
	v_lshlrev_b32_e32 v47, 2, v47
	v_readlane_b32 s8, v254, 49
	s_nop 1
	v_add3_u32 v47, s8, v47, v49
	ds_write_b128 v47, v[26:29]
	ds_write_b128 v47, v[22:25] offset:16
